# v78 + DMA-first only in the 8-read load segments (seg2/seg4); 16-read segments keep ds_reads first
# baseline (speedup 1.0000x reference)
.Lbal_first_21:
	ds_read_b128 v[144:147], v151
	ds_read_b128 v[156:159], v151 offset:1024
	ds_read_b128 v[160:163], v151 offset:2048
	ds_read_b128 v[164:167], v151 offset:3072
	ds_read_b128 v[168:171], v152
	ds_read_b128 v[172:175], v152 offset:1024
	ds_read_b128 v[176:179], v152 offset:2048
	ds_read_b128 v[180:183], v152 offset:3072
	s_add_u32 s26, s24, 0xfffc0080
	s_addc_u32 s27, s25, -1
	s_cmp_eq_u32 s55, 12
	s_cselect_b32 s29, s19, s27
	s_cselect_b32 s28, s51, s26
	s_cselect_b32 s27, s17, s54
	s_cselect_b32 s26, s52, s53
	s_add_i32 m0, s38, 0xc000
	ds_read_b128 v[184:187], v153
	ds_read_b128 v[188:191], v153 offset:1024
	ds_read_b128 v[192:195], v153 offset:2048
	ds_read_b128 v[196:199], v153 offset:3072
	ds_read_b128 v[200:203], v153 offset:4096
	ds_read_b128 v[208:211], v153 offset:5120
	ds_read_b128 v[212:215], v153 offset:6144
	ds_read_b128 v[216:219], v153 offset:7168
	global_load_lds_dwordx4 v138, s[24:25]
	s_add_i32 m0, s38, 0xe000
	s_nop 0
	global_load_lds_dwordx4 v136, s[24:25]
	s_waitcnt vmcnt(8)
	s_waitcnt lgkmcnt(0)
	s_barrier
	s_waitcnt lgkmcnt(0)
	v_mfma_f32_16x16x32_bf16 v[124:127], v[144:147], v[184:187], v[124:127]
	v_mfma_f32_16x16x32_bf16 v[120:123], v[160:163], v[184:187], v[120:123]
	v_mfma_f32_16x16x32_bf16 v[108:111], v[144:147], v[192:195], v[108:111]
	v_mfma_f32_16x16x32_bf16 v[104:107], v[160:163], v[192:195], v[104:107]
	v_mfma_f32_16x16x32_bf16 v[92:95], v[144:147], v[200:203], v[92:95]
	v_mfma_f32_16x16x32_bf16 v[88:91], v[160:163], v[200:203], v[88:91]
	v_mfma_f32_16x16x32_bf16 v[76:79], v[144:147], v[212:215], v[76:79]
	v_mfma_f32_16x16x32_bf16 v[72:75], v[160:163], v[212:215], v[72:75]
	v_mfma_f32_16x16x32_bf16 v[124:127], v[156:159], v[188:191], v[124:127]
	v_mfma_f32_16x16x32_bf16 v[120:123], v[164:167], v[188:191], v[120:123]
	v_mfma_f32_16x16x32_bf16 v[108:111], v[156:159], v[196:199], v[108:111]
	v_mfma_f32_16x16x32_bf16 v[104:107], v[164:167], v[196:199], v[104:107]
	v_mfma_f32_16x16x32_bf16 v[92:95], v[156:159], v[208:211], v[92:95]
	v_mfma_f32_16x16x32_bf16 v[88:91], v[164:167], v[208:211], v[88:91]
	v_mfma_f32_16x16x32_bf16 v[76:79], v[156:159], v[216:219], v[76:79]
	v_mfma_f32_16x16x32_bf16 v[72:75], v[164:167], v[216:219], v[72:75]
	v_mfma_f32_16x16x32_bf16 v[116:119], v[168:171], v[184:187], v[116:119]
	v_mfma_f32_16x16x32_bf16 v[112:115], v[176:179], v[184:187], v[112:115]
	v_mfma_f32_16x16x32_bf16 v[100:103], v[168:171], v[192:195], v[100:103]
	v_mfma_f32_16x16x32_bf16 v[96:99], v[176:179], v[192:195], v[96:99]
	v_mfma_f32_16x16x32_bf16 v[84:87], v[168:171], v[200:203], v[84:87]
	v_mfma_f32_16x16x32_bf16 v[80:83], v[176:179], v[200:203], v[80:83]
	v_mfma_f32_16x16x32_bf16 v[68:71], v[168:171], v[212:215], v[68:71]
	v_mfma_f32_16x16x32_bf16 v[64:67], v[176:179], v[212:215], v[64:67]
	v_mfma_f32_16x16x32_bf16 v[116:119], v[172:175], v[188:191], v[116:119]
	v_mfma_f32_16x16x32_bf16 v[112:115], v[180:183], v[188:191], v[112:115]
	v_mfma_f32_16x16x32_bf16 v[100:103], v[172:175], v[196:199], v[100:103]
	v_mfma_f32_16x16x32_bf16 v[96:99], v[180:183], v[196:199], v[96:99]
	v_mfma_f32_16x16x32_bf16 v[84:87], v[172:175], v[208:211], v[84:87]
	v_mfma_f32_16x16x32_bf16 v[80:83], v[180:183], v[208:211], v[80:83]
	v_mfma_f32_16x16x32_bf16 v[68:71], v[172:175], v[216:219], v[68:71]
	v_mfma_f32_16x16x32_bf16 v[64:67], v[180:183], v[216:219], v[64:67]
	s_barrier
	s_add_i32 s56, s48, s35
	s_mov_b32 m0, s56
	s_nop 0
	global_load_lds_dwordx4 v132, s[26:27]
	s_add_i32 m0, s56, 0x2000
	s_add_u32 s56, s26, 0x40000
	s_mov_b64 s[98:99], s[26:27]
	s_addc_u32 s57, s27, 0
	s_add_i32 s58, s49, s35
	global_load_lds_dwordx4 v128, s[26:27]
	s_mov_b32 m0, s58
	s_mov_b64 s[100:101], s[28:29]
	global_load_lds_dwordx4 v132, s[56:57]
	s_add_i32 m0, s58, 0x2000
	s_nop 0
	global_load_lds_dwordx4 v128, s[56:57]
	ds_read_b128 v[184:187], v153 offset:16384
	ds_read_b128 v[188:191], v153 offset:17408
	ds_read_b128 v[192:195], v153 offset:18432
	ds_read_b128 v[196:199], v153 offset:19456
	ds_read_b128 v[200:203], v153 offset:20480
	ds_read_b128 v[208:211], v153 offset:21504
	ds_read_b128 v[212:215], v153 offset:22528
	ds_read_b128 v[216:219], v153 offset:23552
	s_waitcnt vmcnt(6)
	s_waitcnt lgkmcnt(0)
	s_barrier
	s_waitcnt lgkmcnt(0)
	v_mfma_f32_16x16x32_bf16 v[60:63], v[144:147], v[184:187], v[60:63]
	v_mfma_f32_16x16x32_bf16 v[56:59], v[160:163], v[184:187], v[56:59]
	v_mfma_f32_16x16x32_bf16 v[44:47], v[144:147], v[192:195], v[44:47]
	v_mfma_f32_16x16x32_bf16 v[40:43], v[160:163], v[192:195], v[40:43]
	v_mfma_f32_16x16x32_bf16 v[28:31], v[144:147], v[200:203], v[28:31]
	v_mfma_f32_16x16x32_bf16 v[24:27], v[160:163], v[200:203], v[24:27]
	v_mfma_f32_16x16x32_bf16 v[12:15], v[144:147], v[212:215], v[12:15]
	v_mfma_f32_16x16x32_bf16 v[8:11], v[160:163], v[212:215], v[8:11]
	v_mfma_f32_16x16x32_bf16 v[60:63], v[156:159], v[188:191], v[60:63]
	v_mfma_f32_16x16x32_bf16 v[56:59], v[164:167], v[188:191], v[56:59]
	v_mfma_f32_16x16x32_bf16 v[44:47], v[156:159], v[196:199], v[44:47]
	v_mfma_f32_16x16x32_bf16 v[40:43], v[164:167], v[196:199], v[40:43]
	v_mfma_f32_16x16x32_bf16 v[28:31], v[156:159], v[208:211], v[28:31]
	v_mfma_f32_16x16x32_bf16 v[24:27], v[164:167], v[208:211], v[24:27]
	v_mfma_f32_16x16x32_bf16 v[12:15], v[156:159], v[216:219], v[12:15]
	v_mfma_f32_16x16x32_bf16 v[8:11], v[164:167], v[216:219], v[8:11]
	v_mfma_f32_16x16x32_bf16 v[52:55], v[168:171], v[184:187], v[52:55]
	v_mfma_f32_16x16x32_bf16 v[48:51], v[176:179], v[184:187], v[48:51]
	v_mfma_f32_16x16x32_bf16 v[36:39], v[168:171], v[192:195], v[36:39]
	v_mfma_f32_16x16x32_bf16 v[32:35], v[176:179], v[192:195], v[32:35]
	v_mfma_f32_16x16x32_bf16 v[20:23], v[168:171], v[200:203], v[20:23]
	v_mfma_f32_16x16x32_bf16 v[16:19], v[176:179], v[200:203], v[16:19]
	v_mfma_f32_16x16x32_bf16 v[4:7], v[168:171], v[212:215], v[4:7]
	v_mfma_f32_16x16x32_bf16 v[0:3], v[176:179], v[212:215], v[0:3]
	v_mfma_f32_16x16x32_bf16 v[52:55], v[172:175], v[188:191], v[52:55]
	v_mfma_f32_16x16x32_bf16 v[48:51], v[180:183], v[188:191], v[48:51]
	v_mfma_f32_16x16x32_bf16 v[36:39], v[172:175], v[196:199], v[36:39]
	v_mfma_f32_16x16x32_bf16 v[32:35], v[180:183], v[196:199], v[32:35]
	v_mfma_f32_16x16x32_bf16 v[20:23], v[172:175], v[208:211], v[20:23]
	v_mfma_f32_16x16x32_bf16 v[16:19], v[180:183], v[208:211], v[16:19]
	v_mfma_f32_16x16x32_bf16 v[4:7], v[172:175], v[216:219], v[4:7]
	v_mfma_f32_16x16x32_bf16 v[0:3], v[180:183], v[216:219], v[0:3]
	s_barrier
	s_mov_b32 m0, s38
	s_nop 0
	global_load_lds_dwordx4 v134, s[28:29]
	s_mov_b32 m0, s39
	s_nop 0
	global_load_lds_dwordx4 v130, s[28:29]
	s_add_i32 s56, 0, 0x18000
	s_add_i32 s57, 0, 0x1c000
	v_add_u32_e32 v164, s56, v149
	v_add_u32_e32 v180, s57, v149
	ds_read_b128 v[144:147], v164
	ds_read_b128 v[156:159], v164 offset:1024
	ds_read_b128 v[160:163], v164 offset:2048
	ds_read_b128 v[164:167], v164 offset:3072
	ds_read_b128 v[168:171], v180
	ds_read_b128 v[172:175], v180 offset:1024
	ds_read_b128 v[176:179], v180 offset:2048
	ds_read_b128 v[180:183], v180 offset:3072
	s_add_u32 s28, s28, 0x40000
	s_addc_u32 s29, s29, 0
	s_mov_b32 m0, s40
	ds_read_b128 v[184:187], v153 offset:32768
	ds_read_b128 v[188:191], v153 offset:33792
	ds_read_b128 v[192:195], v153 offset:34816
	ds_read_b128 v[196:199], v153 offset:35840
	ds_read_b128 v[200:203], v153 offset:36864
	ds_read_b128 v[208:211], v153 offset:37888
	ds_read_b128 v[212:215], v153 offset:38912
	ds_read_b128 v[216:219], v153 offset:39936
	global_load_lds_dwordx4 v134, s[28:29]
	s_mov_b32 m0, s41
	s_nop 0
	global_load_lds_dwordx4 v130, s[28:29]
	s_waitcnt vmcnt(8)
	s_waitcnt lgkmcnt(0)
	s_barrier
	s_waitcnt lgkmcnt(0)
	v_mfma_f32_16x16x32_bf16 v[124:127], v[144:147], v[184:187], v[124:127]
	v_mfma_f32_16x16x32_bf16 v[120:123], v[160:163], v[184:187], v[120:123]
	v_mfma_f32_16x16x32_bf16 v[108:111], v[144:147], v[192:195], v[108:111]
	v_mfma_f32_16x16x32_bf16 v[104:107], v[160:163], v[192:195], v[104:107]
	v_mfma_f32_16x16x32_bf16 v[92:95], v[144:147], v[200:203], v[92:95]
	v_mfma_f32_16x16x32_bf16 v[88:91], v[160:163], v[200:203], v[88:91]
	v_mfma_f32_16x16x32_bf16 v[76:79], v[144:147], v[212:215], v[76:79]
	v_mfma_f32_16x16x32_bf16 v[72:75], v[160:163], v[212:215], v[72:75]
	v_mfma_f32_16x16x32_bf16 v[124:127], v[156:159], v[188:191], v[124:127]
	v_mfma_f32_16x16x32_bf16 v[120:123], v[164:167], v[188:191], v[120:123]
	v_mfma_f32_16x16x32_bf16 v[108:111], v[156:159], v[196:199], v[108:111]
	v_mfma_f32_16x16x32_bf16 v[104:107], v[164:167], v[196:199], v[104:107]
	v_mfma_f32_16x16x32_bf16 v[92:95], v[156:159], v[208:211], v[92:95]
	v_mfma_f32_16x16x32_bf16 v[88:91], v[164:167], v[208:211], v[88:91]
	v_mfma_f32_16x16x32_bf16 v[76:79], v[156:159], v[216:219], v[76:79]
	v_mfma_f32_16x16x32_bf16 v[72:75], v[164:167], v[216:219], v[72:75]
	v_mfma_f32_16x16x32_bf16 v[116:119], v[168:171], v[184:187], v[116:119]
	v_mfma_f32_16x16x32_bf16 v[112:115], v[176:179], v[184:187], v[112:115]
	v_mfma_f32_16x16x32_bf16 v[100:103], v[168:171], v[192:195], v[100:103]
	v_mfma_f32_16x16x32_bf16 v[96:99], v[176:179], v[192:195], v[96:99]
	v_mfma_f32_16x16x32_bf16 v[84:87], v[168:171], v[200:203], v[84:87]
	v_mfma_f32_16x16x32_bf16 v[80:83], v[176:179], v[200:203], v[80:83]
	v_mfma_f32_16x16x32_bf16 v[68:71], v[168:171], v[212:215], v[68:71]
	v_mfma_f32_16x16x32_bf16 v[64:67], v[176:179], v[212:215], v[64:67]
	v_mfma_f32_16x16x32_bf16 v[116:119], v[172:175], v[188:191], v[116:119]
	v_mfma_f32_16x16x32_bf16 v[112:115], v[180:183], v[188:191], v[112:115]
	v_mfma_f32_16x16x32_bf16 v[100:103], v[172:175], v[196:199], v[100:103]
	v_mfma_f32_16x16x32_bf16 v[96:99], v[180:183], v[196:199], v[96:99]
	v_mfma_f32_16x16x32_bf16 v[84:87], v[172:175], v[208:211], v[84:87]
	v_mfma_f32_16x16x32_bf16 v[80:83], v[180:183], v[208:211], v[80:83]
	v_mfma_f32_16x16x32_bf16 v[68:71], v[172:175], v[216:219], v[68:71]
	v_mfma_f32_16x16x32_bf16 v[64:67], v[180:183], v[216:219], v[64:67]
	s_barrier
	s_add_i32 s28, s56, s35
	s_mov_b32 m0, s28
	s_nop 0
	global_load_lds_dwordx4 v220, s[26:27]
	s_add_i32 m0, s28, 0x2000
	s_add_u32 s26, s26, 0x40080
	s_addc_u32 s27, s27, 0
	s_add_i32 s28, s57, s35
	global_load_lds_dwordx4 v204, s[98:99]
	s_mov_b32 m0, s28
	s_nop 0
	global_load_lds_dwordx4 v132, s[26:27]
	s_add_i32 m0, s28, 0x2000
	s_nop 0
	global_load_lds_dwordx4 v128, s[26:27]
	s_cmp_lg_u32 s55, 12
	s_cbranch_scc1 .Lbal_last_21
	s_mov_b32 m0, s45
	s_nop 0
	global_load_lds_dwordx4 v221, s[100:101]
	s_mov_b32 m0, s46
	s_nop 0
	global_load_lds_dwordx4 v205, s[100:101]

.Lbal_first_20:
	ds_read_b128 v[140:143], v147
	ds_read_b128 v[150:153], v147 offset:1024
	ds_read_b128 v[154:157], v147 offset:2048
	ds_read_b128 v[158:161], v147 offset:3072
	ds_read_b128 v[162:165], v148
	ds_read_b128 v[166:169], v148 offset:1024
	ds_read_b128 v[170:173], v148 offset:2048
	ds_read_b128 v[174:177], v148 offset:3072
	s_add_u32 s30, s28, 0x100
	s_addc_u32 s31, s29, 0
	s_cmp_eq_u32 s58, 12
	s_cselect_b32 s37, s21, s31
	s_cselect_b32 s36, s27, s30
	s_cselect_b32 s35, s19, s57
	s_cselect_b32 s34, s55, s56
	s_add_i32 m0, s44, 0xc000
	ds_read_b128 v[178:181], v149
	ds_read_b128 v[182:185], v149 offset:1024
	ds_read_b128 v[186:189], v149 offset:2048
	ds_read_b128 v[190:193], v149 offset:3072
	ds_read_b128 v[194:197], v149 offset:4096
	ds_read_b128 v[198:201], v149 offset:5120
	ds_read_b128 v[202:205], v149 offset:6144
	ds_read_b128 v[208:211], v149 offset:7168
	global_load_lds_dwordx4 v134, s[28:29]
	s_add_i32 m0, s44, 0xe000
	s_nop 0
	global_load_lds_dwordx4 v132, s[28:29]
	s_waitcnt vmcnt(8)
	s_waitcnt lgkmcnt(0)
	s_barrier
	s_waitcnt lgkmcnt(0)
	v_mfma_f32_16x16x32_bf16 v[124:127], v[140:143], v[178:181], v[124:127]
	v_mfma_f32_16x16x32_bf16 v[120:123], v[154:157], v[178:181], v[120:123]
	v_mfma_f32_16x16x32_bf16 v[108:111], v[140:143], v[186:189], v[108:111]
	v_mfma_f32_16x16x32_bf16 v[104:107], v[154:157], v[186:189], v[104:107]
	v_mfma_f32_16x16x32_bf16 v[92:95], v[140:143], v[194:197], v[92:95]
	v_mfma_f32_16x16x32_bf16 v[88:91], v[154:157], v[194:197], v[88:91]
	v_mfma_f32_16x16x32_bf16 v[76:79], v[140:143], v[202:205], v[76:79]
	v_mfma_f32_16x16x32_bf16 v[72:75], v[154:157], v[202:205], v[72:75]
	v_mfma_f32_16x16x32_bf16 v[124:127], v[150:153], v[182:185], v[124:127]
	v_mfma_f32_16x16x32_bf16 v[120:123], v[158:161], v[182:185], v[120:123]
	v_mfma_f32_16x16x32_bf16 v[108:111], v[150:153], v[190:193], v[108:111]
	v_mfma_f32_16x16x32_bf16 v[104:107], v[158:161], v[190:193], v[104:107]
	v_mfma_f32_16x16x32_bf16 v[92:95], v[150:153], v[198:201], v[92:95]
	v_mfma_f32_16x16x32_bf16 v[88:91], v[158:161], v[198:201], v[88:91]
	v_mfma_f32_16x16x32_bf16 v[76:79], v[150:153], v[208:211], v[76:79]
	v_mfma_f32_16x16x32_bf16 v[72:75], v[158:161], v[208:211], v[72:75]
	v_mfma_f32_16x16x32_bf16 v[116:119], v[162:165], v[178:181], v[116:119]
	v_mfma_f32_16x16x32_bf16 v[112:115], v[170:173], v[178:181], v[112:115]
	v_mfma_f32_16x16x32_bf16 v[100:103], v[162:165], v[186:189], v[100:103]
	v_mfma_f32_16x16x32_bf16 v[96:99], v[170:173], v[186:189], v[96:99]
	v_mfma_f32_16x16x32_bf16 v[84:87], v[162:165], v[194:197], v[84:87]
	v_mfma_f32_16x16x32_bf16 v[80:83], v[170:173], v[194:197], v[80:83]
	v_mfma_f32_16x16x32_bf16 v[68:71], v[162:165], v[202:205], v[68:71]
	v_mfma_f32_16x16x32_bf16 v[64:67], v[170:173], v[202:205], v[64:67]
	v_mfma_f32_16x16x32_bf16 v[116:119], v[166:169], v[182:185], v[116:119]
	v_mfma_f32_16x16x32_bf16 v[112:115], v[174:177], v[182:185], v[112:115]
	v_mfma_f32_16x16x32_bf16 v[100:103], v[166:169], v[190:193], v[100:103]
	v_mfma_f32_16x16x32_bf16 v[96:99], v[174:177], v[190:193], v[96:99]
	v_mfma_f32_16x16x32_bf16 v[84:87], v[166:169], v[198:201], v[84:87]
	v_mfma_f32_16x16x32_bf16 v[80:83], v[174:177], v[198:201], v[80:83]
	v_mfma_f32_16x16x32_bf16 v[68:71], v[166:169], v[208:211], v[68:71]
	v_mfma_f32_16x16x32_bf16 v[64:67], v[174:177], v[208:211], v[64:67]
	s_barrier
	s_add_i32 s28, s52, s43
	s_mov_b32 m0, s28
	s_nop 0
	global_load_lds_dwordx4 v128, s[34:35]
	s_add_i32 m0, s28, 0x2000
	s_add_u32 s28, s34, 0x40000
	s_mov_b64 s[98:99], s[34:35]
	s_addc_u32 s29, s35, 0
	s_add_i32 s59, s53, s43
	global_load_lds_dwordx4 v130, s[34:35]
	s_mov_b32 m0, s59
	s_nop 0
	global_load_lds_dwordx4 v128, s[28:29]
	s_add_i32 m0, s59, 0x2000
	s_nop 0
	global_load_lds_dwordx4 v130, s[28:29]
	ds_read_b128 v[178:181], v149 offset:16384
	ds_read_b128 v[182:185], v149 offset:17408
	ds_read_b128 v[186:189], v149 offset:18432
	ds_read_b128 v[190:193], v149 offset:19456
	ds_read_b128 v[194:197], v149 offset:20480
	ds_read_b128 v[198:201], v149 offset:21504
	ds_read_b128 v[202:205], v149 offset:22528
	ds_read_b128 v[208:211], v149 offset:23552
	s_waitcnt vmcnt(6)
	s_waitcnt lgkmcnt(0)
	s_barrier
	s_waitcnt lgkmcnt(0)
	v_mfma_f32_16x16x32_bf16 v[60:63], v[140:143], v[178:181], v[60:63]
	v_mfma_f32_16x16x32_bf16 v[56:59], v[154:157], v[178:181], v[56:59]
	v_mfma_f32_16x16x32_bf16 v[44:47], v[140:143], v[186:189], v[44:47]
	v_mfma_f32_16x16x32_bf16 v[40:43], v[154:157], v[186:189], v[40:43]
	v_mfma_f32_16x16x32_bf16 v[28:31], v[140:143], v[194:197], v[28:31]
	v_mfma_f32_16x16x32_bf16 v[24:27], v[154:157], v[194:197], v[24:27]
	v_mfma_f32_16x16x32_bf16 v[12:15], v[140:143], v[202:205], v[12:15]
	v_mfma_f32_16x16x32_bf16 v[8:11], v[154:157], v[202:205], v[8:11]
	v_mfma_f32_16x16x32_bf16 v[60:63], v[150:153], v[182:185], v[60:63]
	v_mfma_f32_16x16x32_bf16 v[56:59], v[158:161], v[182:185], v[56:59]
	v_mfma_f32_16x16x32_bf16 v[44:47], v[150:153], v[190:193], v[44:47]
	v_mfma_f32_16x16x32_bf16 v[40:43], v[158:161], v[190:193], v[40:43]
	v_mfma_f32_16x16x32_bf16 v[28:31], v[150:153], v[198:201], v[28:31]
	v_mfma_f32_16x16x32_bf16 v[24:27], v[158:161], v[198:201], v[24:27]
	v_mfma_f32_16x16x32_bf16 v[12:15], v[150:153], v[208:211], v[12:15]
	v_mfma_f32_16x16x32_bf16 v[8:11], v[158:161], v[208:211], v[8:11]
	v_mfma_f32_16x16x32_bf16 v[52:55], v[162:165], v[178:181], v[52:55]
	v_mfma_f32_16x16x32_bf16 v[48:51], v[170:173], v[178:181], v[48:51]
	v_mfma_f32_16x16x32_bf16 v[36:39], v[162:165], v[186:189], v[36:39]
	v_mfma_f32_16x16x32_bf16 v[32:35], v[170:173], v[186:189], v[32:35]
	v_mfma_f32_16x16x32_bf16 v[20:23], v[162:165], v[194:197], v[20:23]
	v_mfma_f32_16x16x32_bf16 v[16:19], v[170:173], v[194:197], v[16:19]
	v_mfma_f32_16x16x32_bf16 v[4:7], v[162:165], v[202:205], v[4:7]
	v_mfma_f32_16x16x32_bf16 v[0:3], v[170:173], v[202:205], v[0:3]
	v_mfma_f32_16x16x32_bf16 v[52:55], v[166:169], v[182:185], v[52:55]
	v_mfma_f32_16x16x32_bf16 v[48:51], v[174:177], v[182:185], v[48:51]
	v_mfma_f32_16x16x32_bf16 v[36:39], v[166:169], v[190:193], v[36:39]
	v_mfma_f32_16x16x32_bf16 v[32:35], v[174:177], v[190:193], v[32:35]
	v_mfma_f32_16x16x32_bf16 v[20:23], v[166:169], v[198:201], v[20:23]
	v_mfma_f32_16x16x32_bf16 v[16:19], v[174:177], v[198:201], v[16:19]
	v_mfma_f32_16x16x32_bf16 v[4:7], v[166:169], v[208:211], v[4:7]
	v_mfma_f32_16x16x32_bf16 v[0:3], v[174:177], v[208:211], v[0:3]
	s_barrier
	s_mov_b32 m0, s44
	s_nop 0
	global_load_lds_dwordx4 v128, s[36:37]
	s_mov_b32 m0, s45
	s_nop 0
	global_load_lds_dwordx4 v130, s[36:37]
	s_add_i32 s59, 0, 0x18000
	s_add_i32 s60, 0, 0x1c000
	v_add_u32_e32 v158, s59, v145
	v_add_u32_e32 v174, s60, v145
	ds_read_b128 v[140:143], v158
	ds_read_b128 v[150:153], v158 offset:1024
	ds_read_b128 v[154:157], v158 offset:2048
	ds_read_b128 v[158:161], v158 offset:3072
	ds_read_b128 v[162:165], v174
	ds_read_b128 v[166:169], v174 offset:1024
	ds_read_b128 v[170:173], v174 offset:2048
	ds_read_b128 v[174:177], v174 offset:3072
	s_add_u32 s28, s36, 0x40000
	s_addc_u32 s29, s37, 0
	s_mov_b32 m0, s46
	ds_read_b128 v[178:181], v149 offset:32768
	ds_read_b128 v[182:185], v149 offset:33792
	ds_read_b128 v[186:189], v149 offset:34816
	ds_read_b128 v[190:193], v149 offset:35840
	ds_read_b128 v[194:197], v149 offset:36864
	ds_read_b128 v[198:201], v149 offset:37888
	ds_read_b128 v[202:205], v149 offset:38912
	ds_read_b128 v[208:211], v149 offset:39936
	global_load_lds_dwordx4 v128, s[28:29]
	s_mov_b32 m0, s47
	s_nop 0
	global_load_lds_dwordx4 v130, s[28:29]
	s_waitcnt vmcnt(8)
	s_waitcnt lgkmcnt(0)
	s_barrier
	s_waitcnt lgkmcnt(0)
	v_mfma_f32_16x16x32_bf16 v[124:127], v[140:143], v[178:181], v[124:127]
	v_mfma_f32_16x16x32_bf16 v[120:123], v[154:157], v[178:181], v[120:123]
	v_mfma_f32_16x16x32_bf16 v[108:111], v[140:143], v[186:189], v[108:111]
	v_mfma_f32_16x16x32_bf16 v[104:107], v[154:157], v[186:189], v[104:107]
	v_mfma_f32_16x16x32_bf16 v[92:95], v[140:143], v[194:197], v[92:95]
	v_mfma_f32_16x16x32_bf16 v[88:91], v[154:157], v[194:197], v[88:91]
	v_mfma_f32_16x16x32_bf16 v[76:79], v[140:143], v[202:205], v[76:79]
	v_mfma_f32_16x16x32_bf16 v[72:75], v[154:157], v[202:205], v[72:75]
	v_mfma_f32_16x16x32_bf16 v[124:127], v[150:153], v[182:185], v[124:127]
	v_mfma_f32_16x16x32_bf16 v[120:123], v[158:161], v[182:185], v[120:123]
	v_mfma_f32_16x16x32_bf16 v[108:111], v[150:153], v[190:193], v[108:111]
	v_mfma_f32_16x16x32_bf16 v[104:107], v[158:161], v[190:193], v[104:107]
	v_mfma_f32_16x16x32_bf16 v[92:95], v[150:153], v[198:201], v[92:95]
	v_mfma_f32_16x16x32_bf16 v[88:91], v[158:161], v[198:201], v[88:91]
	v_mfma_f32_16x16x32_bf16 v[76:79], v[150:153], v[208:211], v[76:79]
	v_mfma_f32_16x16x32_bf16 v[72:75], v[158:161], v[208:211], v[72:75]
	v_mfma_f32_16x16x32_bf16 v[116:119], v[162:165], v[178:181], v[116:119]
	v_mfma_f32_16x16x32_bf16 v[112:115], v[170:173], v[178:181], v[112:115]
	v_mfma_f32_16x16x32_bf16 v[100:103], v[162:165], v[186:189], v[100:103]
	v_mfma_f32_16x16x32_bf16 v[96:99], v[170:173], v[186:189], v[96:99]
	v_mfma_f32_16x16x32_bf16 v[84:87], v[162:165], v[194:197], v[84:87]
	v_mfma_f32_16x16x32_bf16 v[80:83], v[170:173], v[194:197], v[80:83]
	v_mfma_f32_16x16x32_bf16 v[68:71], v[162:165], v[202:205], v[68:71]
	v_mfma_f32_16x16x32_bf16 v[64:67], v[170:173], v[202:205], v[64:67]
	v_mfma_f32_16x16x32_bf16 v[116:119], v[166:169], v[182:185], v[116:119]
	v_mfma_f32_16x16x32_bf16 v[112:115], v[174:177], v[182:185], v[112:115]
	v_mfma_f32_16x16x32_bf16 v[100:103], v[166:169], v[190:193], v[100:103]
	v_mfma_f32_16x16x32_bf16 v[96:99], v[174:177], v[190:193], v[96:99]
	v_mfma_f32_16x16x32_bf16 v[84:87], v[166:169], v[198:201], v[84:87]
	v_mfma_f32_16x16x32_bf16 v[80:83], v[174:177], v[198:201], v[80:83]
	v_mfma_f32_16x16x32_bf16 v[68:71], v[166:169], v[208:211], v[68:71]
	v_mfma_f32_16x16x32_bf16 v[64:67], v[174:177], v[208:211], v[64:67]
	s_barrier
	s_add_i32 s28, s59, s43
	s_mov_b32 m0, s28
	s_nop 0
	global_load_lds_dwordx4 v212, s[34:35]
	s_add_i32 m0, s28, 0x2000
	s_add_u32 s28, s34, 0x40080
	s_addc_u32 s29, s35, 0
	s_add_i32 s34, s60, s43
	global_load_lds_dwordx4 v213, s[98:99]
	s_mov_b32 m0, s34
	s_nop 0
	global_load_lds_dwordx4 v128, s[28:29]
	s_add_i32 m0, s34, 0x2000
	s_nop 0
	global_load_lds_dwordx4 v130, s[28:29]
	s_cmp_lg_u32 s58, 12
	s_cbranch_scc1 .Lbal_last_20
	s_mov_b32 m0, s49
	s_nop 0
	global_load_lds_dwordx4 v212, s[36:37]
	s_mov_b32 m0, s50
	s_nop 0
	global_load_lds_dwordx4 v213, s[36:37]

.Lbal_first_19:
	ds_read_b128 v[144:147], v151
	ds_read_b128 v[156:159], v151 offset:1024
	ds_read_b128 v[160:163], v151 offset:2048
	ds_read_b128 v[164:167], v151 offset:3072
	ds_read_b128 v[168:171], v152
	ds_read_b128 v[172:175], v152 offset:1024
	ds_read_b128 v[176:179], v152 offset:2048
	ds_read_b128 v[180:183], v152 offset:3072
	s_add_u32 s28, s26, 0xfffc0080
	s_addc_u32 s29, s27, -1
	s_cmp_eq_u32 s53, 12
	s_cselect_b32 s31, s21, s29
	s_cselect_b32 s30, s49, s28
	s_cselect_b32 s29, s19, s52
	s_cselect_b32 s28, s50, s51
	s_add_i32 m0, s39, 0xc000
	ds_read_b128 v[184:187], v153
	ds_read_b128 v[188:191], v153 offset:1024
	ds_read_b128 v[192:195], v153 offset:2048
	ds_read_b128 v[196:199], v153 offset:3072
	ds_read_b128 v[200:203], v153 offset:4096
	ds_read_b128 v[208:211], v153 offset:5120
	ds_read_b128 v[212:215], v153 offset:6144
	ds_read_b128 v[216:219], v153 offset:7168
	global_load_lds_dwordx4 v138, s[26:27]
	s_add_i32 m0, s39, 0xe000
	s_nop 0
	global_load_lds_dwordx4 v136, s[26:27]
	s_waitcnt vmcnt(8)
	s_waitcnt lgkmcnt(0)
	s_barrier
	s_waitcnt lgkmcnt(0)
	v_mfma_f32_16x16x32_bf16 v[124:127], v[144:147], v[184:187], v[124:127]
	v_mfma_f32_16x16x32_bf16 v[120:123], v[160:163], v[184:187], v[120:123]
	v_mfma_f32_16x16x32_bf16 v[108:111], v[144:147], v[192:195], v[108:111]
	v_mfma_f32_16x16x32_bf16 v[104:107], v[160:163], v[192:195], v[104:107]
	v_mfma_f32_16x16x32_bf16 v[92:95], v[144:147], v[200:203], v[92:95]
	v_mfma_f32_16x16x32_bf16 v[88:91], v[160:163], v[200:203], v[88:91]
	v_mfma_f32_16x16x32_bf16 v[76:79], v[144:147], v[212:215], v[76:79]
	v_mfma_f32_16x16x32_bf16 v[72:75], v[160:163], v[212:215], v[72:75]
	v_mfma_f32_16x16x32_bf16 v[124:127], v[156:159], v[188:191], v[124:127]
	v_mfma_f32_16x16x32_bf16 v[120:123], v[164:167], v[188:191], v[120:123]
	v_mfma_f32_16x16x32_bf16 v[108:111], v[156:159], v[196:199], v[108:111]
	v_mfma_f32_16x16x32_bf16 v[104:107], v[164:167], v[196:199], v[104:107]
	v_mfma_f32_16x16x32_bf16 v[92:95], v[156:159], v[208:211], v[92:95]
	v_mfma_f32_16x16x32_bf16 v[88:91], v[164:167], v[208:211], v[88:91]
	v_mfma_f32_16x16x32_bf16 v[76:79], v[156:159], v[216:219], v[76:79]
	v_mfma_f32_16x16x32_bf16 v[72:75], v[164:167], v[216:219], v[72:75]
	v_mfma_f32_16x16x32_bf16 v[116:119], v[168:171], v[184:187], v[116:119]
	v_mfma_f32_16x16x32_bf16 v[112:115], v[176:179], v[184:187], v[112:115]
	v_mfma_f32_16x16x32_bf16 v[100:103], v[168:171], v[192:195], v[100:103]
	v_mfma_f32_16x16x32_bf16 v[96:99], v[176:179], v[192:195], v[96:99]
	v_mfma_f32_16x16x32_bf16 v[84:87], v[168:171], v[200:203], v[84:87]
	v_mfma_f32_16x16x32_bf16 v[80:83], v[176:179], v[200:203], v[80:83]
	v_mfma_f32_16x16x32_bf16 v[68:71], v[168:171], v[212:215], v[68:71]
	v_mfma_f32_16x16x32_bf16 v[64:67], v[176:179], v[212:215], v[64:67]
	v_mfma_f32_16x16x32_bf16 v[116:119], v[172:175], v[188:191], v[116:119]
	v_mfma_f32_16x16x32_bf16 v[112:115], v[180:183], v[188:191], v[112:115]
	v_mfma_f32_16x16x32_bf16 v[100:103], v[172:175], v[196:199], v[100:103]
	v_mfma_f32_16x16x32_bf16 v[96:99], v[180:183], v[196:199], v[96:99]
	v_mfma_f32_16x16x32_bf16 v[84:87], v[172:175], v[208:211], v[84:87]
	v_mfma_f32_16x16x32_bf16 v[80:83], v[180:183], v[208:211], v[80:83]
	v_mfma_f32_16x16x32_bf16 v[68:71], v[172:175], v[216:219], v[68:71]
	v_mfma_f32_16x16x32_bf16 v[64:67], v[180:183], v[216:219], v[64:67]
	s_barrier
	s_add_i32 s54, s46, s38
	s_mov_b32 m0, s54
	s_nop 0
	global_load_lds_dwordx4 v130, s[28:29]
	s_add_i32 m0, s54, 0x2000
	s_add_u32 s54, s28, 0x40000
	s_mov_b64 s[98:99], s[28:29]
	s_addc_u32 s55, s29, 0
	s_add_i32 s56, s47, s38
	global_load_lds_dwordx4 v134, s[28:29]
	s_mov_b32 m0, s56
	s_mov_b64 s[100:101], s[30:31]
	global_load_lds_dwordx4 v130, s[54:55]
	s_add_i32 m0, s56, 0x2000
	s_nop 0
	global_load_lds_dwordx4 v134, s[54:55]
	ds_read_b128 v[184:187], v153 offset:16384
	ds_read_b128 v[188:191], v153 offset:17408
	ds_read_b128 v[192:195], v153 offset:18432
	ds_read_b128 v[196:199], v153 offset:19456
	ds_read_b128 v[200:203], v153 offset:20480
	ds_read_b128 v[208:211], v153 offset:21504
	ds_read_b128 v[212:215], v153 offset:22528
	ds_read_b128 v[216:219], v153 offset:23552
	s_waitcnt vmcnt(6)
	s_waitcnt lgkmcnt(0)
	s_barrier
	s_waitcnt lgkmcnt(0)
	v_mfma_f32_16x16x32_bf16 v[60:63], v[144:147], v[184:187], v[60:63]
	v_mfma_f32_16x16x32_bf16 v[56:59], v[160:163], v[184:187], v[56:59]
	v_mfma_f32_16x16x32_bf16 v[44:47], v[144:147], v[192:195], v[44:47]
	v_mfma_f32_16x16x32_bf16 v[40:43], v[160:163], v[192:195], v[40:43]
	v_mfma_f32_16x16x32_bf16 v[28:31], v[144:147], v[200:203], v[28:31]
	v_mfma_f32_16x16x32_bf16 v[24:27], v[160:163], v[200:203], v[24:27]
	v_mfma_f32_16x16x32_bf16 v[12:15], v[144:147], v[212:215], v[12:15]
	v_mfma_f32_16x16x32_bf16 v[8:11], v[160:163], v[212:215], v[8:11]
	v_mfma_f32_16x16x32_bf16 v[60:63], v[156:159], v[188:191], v[60:63]
	v_mfma_f32_16x16x32_bf16 v[56:59], v[164:167], v[188:191], v[56:59]
	v_mfma_f32_16x16x32_bf16 v[44:47], v[156:159], v[196:199], v[44:47]
	v_mfma_f32_16x16x32_bf16 v[40:43], v[164:167], v[196:199], v[40:43]
	v_mfma_f32_16x16x32_bf16 v[28:31], v[156:159], v[208:211], v[28:31]
	v_mfma_f32_16x16x32_bf16 v[24:27], v[164:167], v[208:211], v[24:27]
	v_mfma_f32_16x16x32_bf16 v[12:15], v[156:159], v[216:219], v[12:15]
	v_mfma_f32_16x16x32_bf16 v[8:11], v[164:167], v[216:219], v[8:11]
	v_mfma_f32_16x16x32_bf16 v[52:55], v[168:171], v[184:187], v[52:55]
	v_mfma_f32_16x16x32_bf16 v[48:51], v[176:179], v[184:187], v[48:51]
	v_mfma_f32_16x16x32_bf16 v[36:39], v[168:171], v[192:195], v[36:39]
	v_mfma_f32_16x16x32_bf16 v[32:35], v[176:179], v[192:195], v[32:35]
	v_mfma_f32_16x16x32_bf16 v[20:23], v[168:171], v[200:203], v[20:23]
	v_mfma_f32_16x16x32_bf16 v[16:19], v[176:179], v[200:203], v[16:19]
	v_mfma_f32_16x16x32_bf16 v[4:7], v[168:171], v[212:215], v[4:7]
	v_mfma_f32_16x16x32_bf16 v[0:3], v[176:179], v[212:215], v[0:3]
	v_mfma_f32_16x16x32_bf16 v[52:55], v[172:175], v[188:191], v[52:55]
	v_mfma_f32_16x16x32_bf16 v[48:51], v[180:183], v[188:191], v[48:51]
	v_mfma_f32_16x16x32_bf16 v[36:39], v[172:175], v[196:199], v[36:39]
	v_mfma_f32_16x16x32_bf16 v[32:35], v[180:183], v[196:199], v[32:35]
	v_mfma_f32_16x16x32_bf16 v[20:23], v[172:175], v[208:211], v[20:23]
	v_mfma_f32_16x16x32_bf16 v[16:19], v[180:183], v[208:211], v[16:19]
	v_mfma_f32_16x16x32_bf16 v[4:7], v[172:175], v[216:219], v[4:7]
	v_mfma_f32_16x16x32_bf16 v[0:3], v[180:183], v[216:219], v[0:3]
	s_barrier
	s_mov_b32 m0, s39
	s_nop 0
	global_load_lds_dwordx4 v128, s[30:31]
	s_mov_b32 m0, s40
	s_nop 0
	global_load_lds_dwordx4 v132, s[30:31]
	s_add_i32 s54, 0, 0x18000
	v_add_u32_e32 v155, s54, v149
	s_add_i32 s55, 0, 0x1c000
	ds_read_b128 v[144:147], v155
	ds_read_b128 v[156:159], v155 offset:1024
	ds_read_b128 v[160:163], v155 offset:2048
	ds_read_b128 v[164:167], v155 offset:3072
	v_add_u32_e32 v155, s55, v149
	ds_read_b128 v[168:171], v155
	ds_read_b128 v[172:175], v155 offset:1024
	ds_read_b128 v[176:179], v155 offset:2048
	ds_read_b128 v[180:183], v155 offset:3072
	s_add_u32 s30, s30, 0x40000
	s_addc_u32 s31, s31, 0
	s_mov_b32 m0, s41
	ds_read_b128 v[184:187], v153 offset:32768
	ds_read_b128 v[188:191], v153 offset:33792
	ds_read_b128 v[192:195], v153 offset:34816
	ds_read_b128 v[196:199], v153 offset:35840
	ds_read_b128 v[200:203], v153 offset:36864
	ds_read_b128 v[208:211], v153 offset:37888
	ds_read_b128 v[212:215], v153 offset:38912
	ds_read_b128 v[216:219], v153 offset:39936
	global_load_lds_dwordx4 v128, s[30:31]
	s_mov_b32 m0, s42
	s_nop 0
	global_load_lds_dwordx4 v132, s[30:31]
	s_waitcnt vmcnt(8)
	s_waitcnt lgkmcnt(0)
	s_barrier
	s_waitcnt lgkmcnt(0)
	v_mfma_f32_16x16x32_bf16 v[124:127], v[144:147], v[184:187], v[124:127]
	v_mfma_f32_16x16x32_bf16 v[120:123], v[160:163], v[184:187], v[120:123]
	v_mfma_f32_16x16x32_bf16 v[108:111], v[144:147], v[192:195], v[108:111]
	v_mfma_f32_16x16x32_bf16 v[104:107], v[160:163], v[192:195], v[104:107]
	v_mfma_f32_16x16x32_bf16 v[92:95], v[144:147], v[200:203], v[92:95]
	v_mfma_f32_16x16x32_bf16 v[88:91], v[160:163], v[200:203], v[88:91]
	v_mfma_f32_16x16x32_bf16 v[76:79], v[144:147], v[212:215], v[76:79]
	v_mfma_f32_16x16x32_bf16 v[72:75], v[160:163], v[212:215], v[72:75]
	v_mfma_f32_16x16x32_bf16 v[124:127], v[156:159], v[188:191], v[124:127]
	v_mfma_f32_16x16x32_bf16 v[120:123], v[164:167], v[188:191], v[120:123]
	v_mfma_f32_16x16x32_bf16 v[108:111], v[156:159], v[196:199], v[108:111]
	v_mfma_f32_16x16x32_bf16 v[104:107], v[164:167], v[196:199], v[104:107]
	v_mfma_f32_16x16x32_bf16 v[92:95], v[156:159], v[208:211], v[92:95]
	v_mfma_f32_16x16x32_bf16 v[88:91], v[164:167], v[208:211], v[88:91]
	v_mfma_f32_16x16x32_bf16 v[76:79], v[156:159], v[216:219], v[76:79]
	v_mfma_f32_16x16x32_bf16 v[72:75], v[164:167], v[216:219], v[72:75]
	v_mfma_f32_16x16x32_bf16 v[116:119], v[168:171], v[184:187], v[116:119]
	v_mfma_f32_16x16x32_bf16 v[112:115], v[176:179], v[184:187], v[112:115]
	v_mfma_f32_16x16x32_bf16 v[100:103], v[168:171], v[192:195], v[100:103]
	v_mfma_f32_16x16x32_bf16 v[96:99], v[176:179], v[192:195], v[96:99]
	v_mfma_f32_16x16x32_bf16 v[84:87], v[168:171], v[200:203], v[84:87]
	v_mfma_f32_16x16x32_bf16 v[80:83], v[176:179], v[200:203], v[80:83]
	v_mfma_f32_16x16x32_bf16 v[68:71], v[168:171], v[212:215], v[68:71]
	v_mfma_f32_16x16x32_bf16 v[64:67], v[176:179], v[212:215], v[64:67]
	v_mfma_f32_16x16x32_bf16 v[116:119], v[172:175], v[188:191], v[116:119]
	v_mfma_f32_16x16x32_bf16 v[112:115], v[180:183], v[188:191], v[112:115]
	v_mfma_f32_16x16x32_bf16 v[100:103], v[172:175], v[196:199], v[100:103]
	v_mfma_f32_16x16x32_bf16 v[96:99], v[180:183], v[196:199], v[96:99]
	v_mfma_f32_16x16x32_bf16 v[84:87], v[172:175], v[208:211], v[84:87]
	v_mfma_f32_16x16x32_bf16 v[80:83], v[180:183], v[208:211], v[80:83]
	v_mfma_f32_16x16x32_bf16 v[68:71], v[172:175], v[216:219], v[68:71]
	v_mfma_f32_16x16x32_bf16 v[64:67], v[180:183], v[216:219], v[64:67]
	s_barrier
	s_add_i32 s30, s54, s38
	s_mov_b32 m0, s30
	s_nop 0
	global_load_lds_dwordx4 v205, s[28:29]
	s_add_i32 m0, s30, 0x2000
	s_add_u32 s28, s28, 0x40080
	s_addc_u32 s29, s29, 0
	s_add_i32 s30, s55, s38
	global_load_lds_dwordx4 v221, s[98:99]
	s_mov_b32 m0, s30
	s_nop 0
	global_load_lds_dwordx4 v130, s[28:29]
	s_add_i32 m0, s30, 0x2000
	s_nop 0
	global_load_lds_dwordx4 v134, s[28:29]
	s_cmp_lg_u32 s53, 12
	s_cbranch_scc1 .Lbal_last_19
	s_mov_b32 m0, s44
	s_nop 0
	global_load_lds_dwordx4 v204, s[100:101]
	s_mov_b32 m0, s45
	s_nop 0
	global_load_lds_dwordx4 v220, s[100:101]

.Lbal_first_18:
	ds_read_b128 v[140:143], v147
	ds_read_b128 v[150:153], v147 offset:1024
	ds_read_b128 v[154:157], v147 offset:2048
	ds_read_b128 v[158:161], v147 offset:3072
	ds_read_b128 v[162:165], v148
	ds_read_b128 v[166:169], v148 offset:1024
	ds_read_b128 v[170:173], v148 offset:2048
	ds_read_b128 v[174:177], v148 offset:3072
	s_add_u32 s30, s28, 0x100
	s_addc_u32 s31, s29, 0
	s_cmp_eq_u32 s58, 60
	s_cselect_b32 s37, s21, s31
	s_cselect_b32 s36, s27, s30
	s_cselect_b32 s35, s19, s57
	s_cselect_b32 s34, s55, s56
	s_add_i32 m0, s44, 0xc000
	ds_read_b128 v[178:181], v149
	ds_read_b128 v[182:185], v149 offset:1024
	ds_read_b128 v[186:189], v149 offset:2048
	ds_read_b128 v[190:193], v149 offset:3072
	ds_read_b128 v[194:197], v149 offset:4096
	ds_read_b128 v[198:201], v149 offset:5120
	ds_read_b128 v[202:205], v149 offset:6144
	ds_read_b128 v[208:211], v149 offset:7168
	global_load_lds_dwordx4 v134, s[28:29]
	s_add_i32 m0, s44, 0xe000
	s_nop 0
	global_load_lds_dwordx4 v132, s[28:29]
	s_waitcnt vmcnt(8)
	s_waitcnt lgkmcnt(0)
	s_barrier
	s_waitcnt lgkmcnt(0)
	v_mfma_f32_16x16x32_bf16 v[124:127], v[140:143], v[178:181], v[124:127]
	v_mfma_f32_16x16x32_bf16 v[120:123], v[154:157], v[178:181], v[120:123]
	v_mfma_f32_16x16x32_bf16 v[108:111], v[140:143], v[186:189], v[108:111]
	v_mfma_f32_16x16x32_bf16 v[104:107], v[154:157], v[186:189], v[104:107]
	v_mfma_f32_16x16x32_bf16 v[92:95], v[140:143], v[194:197], v[92:95]
	v_mfma_f32_16x16x32_bf16 v[88:91], v[154:157], v[194:197], v[88:91]
	v_mfma_f32_16x16x32_bf16 v[76:79], v[140:143], v[202:205], v[76:79]
	v_mfma_f32_16x16x32_bf16 v[72:75], v[154:157], v[202:205], v[72:75]
	v_mfma_f32_16x16x32_bf16 v[124:127], v[150:153], v[182:185], v[124:127]
	v_mfma_f32_16x16x32_bf16 v[120:123], v[158:161], v[182:185], v[120:123]
	v_mfma_f32_16x16x32_bf16 v[108:111], v[150:153], v[190:193], v[108:111]
	v_mfma_f32_16x16x32_bf16 v[104:107], v[158:161], v[190:193], v[104:107]
	v_mfma_f32_16x16x32_bf16 v[92:95], v[150:153], v[198:201], v[92:95]
	v_mfma_f32_16x16x32_bf16 v[88:91], v[158:161], v[198:201], v[88:91]
	v_mfma_f32_16x16x32_bf16 v[76:79], v[150:153], v[208:211], v[76:79]
	v_mfma_f32_16x16x32_bf16 v[72:75], v[158:161], v[208:211], v[72:75]
	v_mfma_f32_16x16x32_bf16 v[116:119], v[162:165], v[178:181], v[116:119]
	v_mfma_f32_16x16x32_bf16 v[112:115], v[170:173], v[178:181], v[112:115]
	v_mfma_f32_16x16x32_bf16 v[100:103], v[162:165], v[186:189], v[100:103]
	v_mfma_f32_16x16x32_bf16 v[96:99], v[170:173], v[186:189], v[96:99]
	v_mfma_f32_16x16x32_bf16 v[84:87], v[162:165], v[194:197], v[84:87]
	v_mfma_f32_16x16x32_bf16 v[80:83], v[170:173], v[194:197], v[80:83]
	v_mfma_f32_16x16x32_bf16 v[68:71], v[162:165], v[202:205], v[68:71]
	v_mfma_f32_16x16x32_bf16 v[64:67], v[170:173], v[202:205], v[64:67]
	v_mfma_f32_16x16x32_bf16 v[116:119], v[166:169], v[182:185], v[116:119]
	v_mfma_f32_16x16x32_bf16 v[112:115], v[174:177], v[182:185], v[112:115]
	v_mfma_f32_16x16x32_bf16 v[100:103], v[166:169], v[190:193], v[100:103]
	v_mfma_f32_16x16x32_bf16 v[96:99], v[174:177], v[190:193], v[96:99]
	v_mfma_f32_16x16x32_bf16 v[84:87], v[166:169], v[198:201], v[84:87]
	v_mfma_f32_16x16x32_bf16 v[80:83], v[174:177], v[198:201], v[80:83]
	v_mfma_f32_16x16x32_bf16 v[68:71], v[166:169], v[208:211], v[68:71]
	v_mfma_f32_16x16x32_bf16 v[64:67], v[174:177], v[208:211], v[64:67]
	s_barrier
	s_add_i32 s28, s52, s43
	s_mov_b32 m0, s28
	s_nop 0
	global_load_lds_dwordx4 v128, s[34:35]
	s_add_i32 m0, s28, 0x2000
	s_add_u32 s28, s34, 0x100000
	s_mov_b64 s[98:99], s[34:35]
	s_addc_u32 s29, s35, 0
	s_add_i32 s59, s53, s43
	global_load_lds_dwordx4 v130, s[34:35]
	s_mov_b32 m0, s59
	s_nop 0
	global_load_lds_dwordx4 v128, s[28:29]
	s_add_i32 m0, s59, 0x2000
	s_nop 0
	global_load_lds_dwordx4 v130, s[28:29]
	ds_read_b128 v[178:181], v149 offset:16384
	ds_read_b128 v[182:185], v149 offset:17408
	ds_read_b128 v[186:189], v149 offset:18432
	ds_read_b128 v[190:193], v149 offset:19456
	ds_read_b128 v[194:197], v149 offset:20480
	ds_read_b128 v[198:201], v149 offset:21504
	ds_read_b128 v[202:205], v149 offset:22528
	ds_read_b128 v[208:211], v149 offset:23552
	s_waitcnt vmcnt(6)
	s_waitcnt lgkmcnt(0)
	s_barrier
	s_waitcnt lgkmcnt(0)
	v_mfma_f32_16x16x32_bf16 v[60:63], v[140:143], v[178:181], v[60:63]
	v_mfma_f32_16x16x32_bf16 v[56:59], v[154:157], v[178:181], v[56:59]
	v_mfma_f32_16x16x32_bf16 v[44:47], v[140:143], v[186:189], v[44:47]
	v_mfma_f32_16x16x32_bf16 v[40:43], v[154:157], v[186:189], v[40:43]
	v_mfma_f32_16x16x32_bf16 v[28:31], v[140:143], v[194:197], v[28:31]
	v_mfma_f32_16x16x32_bf16 v[24:27], v[154:157], v[194:197], v[24:27]
	v_mfma_f32_16x16x32_bf16 v[12:15], v[140:143], v[202:205], v[12:15]
	v_mfma_f32_16x16x32_bf16 v[8:11], v[154:157], v[202:205], v[8:11]
	v_mfma_f32_16x16x32_bf16 v[60:63], v[150:153], v[182:185], v[60:63]
	v_mfma_f32_16x16x32_bf16 v[56:59], v[158:161], v[182:185], v[56:59]
	v_mfma_f32_16x16x32_bf16 v[44:47], v[150:153], v[190:193], v[44:47]
	v_mfma_f32_16x16x32_bf16 v[40:43], v[158:161], v[190:193], v[40:43]
	v_mfma_f32_16x16x32_bf16 v[28:31], v[150:153], v[198:201], v[28:31]
	v_mfma_f32_16x16x32_bf16 v[24:27], v[158:161], v[198:201], v[24:27]
	v_mfma_f32_16x16x32_bf16 v[12:15], v[150:153], v[208:211], v[12:15]
	v_mfma_f32_16x16x32_bf16 v[8:11], v[158:161], v[208:211], v[8:11]
	v_mfma_f32_16x16x32_bf16 v[52:55], v[162:165], v[178:181], v[52:55]
	v_mfma_f32_16x16x32_bf16 v[48:51], v[170:173], v[178:181], v[48:51]
	v_mfma_f32_16x16x32_bf16 v[36:39], v[162:165], v[186:189], v[36:39]
	v_mfma_f32_16x16x32_bf16 v[32:35], v[170:173], v[186:189], v[32:35]
	v_mfma_f32_16x16x32_bf16 v[20:23], v[162:165], v[194:197], v[20:23]
	v_mfma_f32_16x16x32_bf16 v[16:19], v[170:173], v[194:197], v[16:19]
	v_mfma_f32_16x16x32_bf16 v[4:7], v[162:165], v[202:205], v[4:7]
	v_mfma_f32_16x16x32_bf16 v[0:3], v[170:173], v[202:205], v[0:3]
	v_mfma_f32_16x16x32_bf16 v[52:55], v[166:169], v[182:185], v[52:55]
	v_mfma_f32_16x16x32_bf16 v[48:51], v[174:177], v[182:185], v[48:51]
	v_mfma_f32_16x16x32_bf16 v[36:39], v[166:169], v[190:193], v[36:39]
	v_mfma_f32_16x16x32_bf16 v[32:35], v[174:177], v[190:193], v[32:35]
	v_mfma_f32_16x16x32_bf16 v[20:23], v[166:169], v[198:201], v[20:23]
	v_mfma_f32_16x16x32_bf16 v[16:19], v[174:177], v[198:201], v[16:19]
	v_mfma_f32_16x16x32_bf16 v[4:7], v[166:169], v[208:211], v[4:7]
	v_mfma_f32_16x16x32_bf16 v[0:3], v[174:177], v[208:211], v[0:3]
	s_barrier
	s_mov_b32 m0, s44
	s_nop 0
	global_load_lds_dwordx4 v128, s[36:37]
	s_mov_b32 m0, s45
	s_nop 0
	global_load_lds_dwordx4 v130, s[36:37]
	s_add_i32 s59, 0, 0x18000
	s_add_i32 s60, 0, 0x1c000
	v_add_u32_e32 v158, s59, v145
	v_add_u32_e32 v174, s60, v145
	ds_read_b128 v[140:143], v158
	ds_read_b128 v[150:153], v158 offset:1024
	ds_read_b128 v[154:157], v158 offset:2048
	ds_read_b128 v[158:161], v158 offset:3072
	ds_read_b128 v[162:165], v174
	ds_read_b128 v[166:169], v174 offset:1024
	ds_read_b128 v[170:173], v174 offset:2048
	ds_read_b128 v[174:177], v174 offset:3072
	s_add_u32 s28, s36, 0x100000
	s_addc_u32 s29, s37, 0
	s_mov_b32 m0, s46
	ds_read_b128 v[178:181], v149 offset:32768
	ds_read_b128 v[182:185], v149 offset:33792
	ds_read_b128 v[186:189], v149 offset:34816
	ds_read_b128 v[190:193], v149 offset:35840
	ds_read_b128 v[194:197], v149 offset:36864
	ds_read_b128 v[198:201], v149 offset:37888
	ds_read_b128 v[202:205], v149 offset:38912
	ds_read_b128 v[208:211], v149 offset:39936
	global_load_lds_dwordx4 v128, s[28:29]
	s_mov_b32 m0, s47
	s_nop 0
	global_load_lds_dwordx4 v130, s[28:29]
	s_waitcnt vmcnt(8)
	s_waitcnt lgkmcnt(0)
	s_barrier
	s_waitcnt lgkmcnt(0)
	v_mfma_f32_16x16x32_bf16 v[124:127], v[140:143], v[178:181], v[124:127]
	v_mfma_f32_16x16x32_bf16 v[120:123], v[154:157], v[178:181], v[120:123]
	v_mfma_f32_16x16x32_bf16 v[108:111], v[140:143], v[186:189], v[108:111]
	v_mfma_f32_16x16x32_bf16 v[104:107], v[154:157], v[186:189], v[104:107]
	v_mfma_f32_16x16x32_bf16 v[92:95], v[140:143], v[194:197], v[92:95]
	v_mfma_f32_16x16x32_bf16 v[88:91], v[154:157], v[194:197], v[88:91]
	v_mfma_f32_16x16x32_bf16 v[76:79], v[140:143], v[202:205], v[76:79]
	v_mfma_f32_16x16x32_bf16 v[72:75], v[154:157], v[202:205], v[72:75]
	v_mfma_f32_16x16x32_bf16 v[124:127], v[150:153], v[182:185], v[124:127]
	v_mfma_f32_16x16x32_bf16 v[120:123], v[158:161], v[182:185], v[120:123]
	v_mfma_f32_16x16x32_bf16 v[108:111], v[150:153], v[190:193], v[108:111]
	v_mfma_f32_16x16x32_bf16 v[104:107], v[158:161], v[190:193], v[104:107]
	v_mfma_f32_16x16x32_bf16 v[92:95], v[150:153], v[198:201], v[92:95]
	v_mfma_f32_16x16x32_bf16 v[88:91], v[158:161], v[198:201], v[88:91]
	v_mfma_f32_16x16x32_bf16 v[76:79], v[150:153], v[208:211], v[76:79]
	v_mfma_f32_16x16x32_bf16 v[72:75], v[158:161], v[208:211], v[72:75]
	v_mfma_f32_16x16x32_bf16 v[116:119], v[162:165], v[178:181], v[116:119]
	v_mfma_f32_16x16x32_bf16 v[112:115], v[170:173], v[178:181], v[112:115]
	v_mfma_f32_16x16x32_bf16 v[100:103], v[162:165], v[186:189], v[100:103]
	v_mfma_f32_16x16x32_bf16 v[96:99], v[170:173], v[186:189], v[96:99]
	v_mfma_f32_16x16x32_bf16 v[84:87], v[162:165], v[194:197], v[84:87]
	v_mfma_f32_16x16x32_bf16 v[80:83], v[170:173], v[194:197], v[80:83]
	v_mfma_f32_16x16x32_bf16 v[68:71], v[162:165], v[202:205], v[68:71]
	v_mfma_f32_16x16x32_bf16 v[64:67], v[170:173], v[202:205], v[64:67]
	v_mfma_f32_16x16x32_bf16 v[116:119], v[166:169], v[182:185], v[116:119]
	v_mfma_f32_16x16x32_bf16 v[112:115], v[174:177], v[182:185], v[112:115]
	v_mfma_f32_16x16x32_bf16 v[100:103], v[166:169], v[190:193], v[100:103]
	v_mfma_f32_16x16x32_bf16 v[96:99], v[174:177], v[190:193], v[96:99]
	v_mfma_f32_16x16x32_bf16 v[84:87], v[166:169], v[198:201], v[84:87]
	v_mfma_f32_16x16x32_bf16 v[80:83], v[174:177], v[198:201], v[80:83]
	v_mfma_f32_16x16x32_bf16 v[68:71], v[166:169], v[208:211], v[68:71]
	v_mfma_f32_16x16x32_bf16 v[64:67], v[174:177], v[208:211], v[64:67]
	s_barrier
	s_add_i32 s28, s59, s43
	s_mov_b32 m0, s28
	s_nop 0
	global_load_lds_dwordx4 v212, s[34:35]
	s_add_i32 m0, s28, 0x2000
	s_add_u32 s28, s34, 0x100080
	s_addc_u32 s29, s35, 0
	s_add_i32 s34, s60, s43
	global_load_lds_dwordx4 v213, s[98:99]
	s_mov_b32 m0, s34
	s_nop 0
	global_load_lds_dwordx4 v128, s[28:29]
	s_add_i32 m0, s34, 0x2000
	s_nop 0
	global_load_lds_dwordx4 v130, s[28:29]
	s_cmp_lg_u32 s58, 60
	s_cbranch_scc1 .Lbal_last_18
	s_mov_b32 m0, s49
	s_nop 0
	global_load_lds_dwordx4 v212, s[36:37]
	s_mov_b32 m0, s50
	s_nop 0
	global_load_lds_dwordx4 v213, s[36:37]

.Lbal_first_17:
	ds_read_b128 v[140:143], v153
	ds_read_b128 v[144:147], v153 offset:1024
	ds_read_b128 v[158:161], v153 offset:2048
	ds_read_b128 v[162:165], v153 offset:3072
	ds_read_b128 v[166:169], v154
	ds_read_b128 v[170:173], v154 offset:1024
	ds_read_b128 v[174:177], v154 offset:2048
	ds_read_b128 v[178:181], v154 offset:3072
	s_add_u32 s38, s36, 0xfffc0080
	s_addc_u32 s39, s37, -1
	s_cmp_eq_u32 s61, 12
	s_cselect_b32 s41, s3, s39
	s_cselect_b32 s40, s29, s38
	s_cselect_b32 s39, s27, s60
	s_cselect_b32 s38, s58, s59
	s_add_i32 m0, s46, 0xc000
	ds_read_b128 v[182:185], v155
	ds_read_b128 v[186:189], v155 offset:1024
	ds_read_b128 v[190:193], v155 offset:2048
	ds_read_b128 v[194:197], v155 offset:3072
	ds_read_b128 v[198:201], v155 offset:4096
	ds_read_b128 v[202:205], v155 offset:5120
	ds_read_b128 v[208:211], v155 offset:6144
	ds_read_b128 v[212:215], v155 offset:7168
	global_load_lds_dwordx4 v134, s[36:37]
	s_add_i32 m0, s46, 0xe000
	s_nop 0
	global_load_lds_dwordx4 v132, s[36:37]
	s_waitcnt vmcnt(8)
	s_waitcnt lgkmcnt(0)
	s_barrier
	s_waitcnt lgkmcnt(0)
	v_mfma_f32_16x16x32_bf16 v[124:127], v[140:143], v[182:185], v[124:127]
	v_mfma_f32_16x16x32_bf16 v[120:123], v[158:161], v[182:185], v[120:123]
	v_mfma_f32_16x16x32_bf16 v[108:111], v[140:143], v[190:193], v[108:111]
	v_mfma_f32_16x16x32_bf16 v[104:107], v[158:161], v[190:193], v[104:107]
	v_mfma_f32_16x16x32_bf16 v[92:95], v[140:143], v[198:201], v[92:95]
	v_mfma_f32_16x16x32_bf16 v[88:91], v[158:161], v[198:201], v[88:91]
	v_mfma_f32_16x16x32_bf16 v[76:79], v[140:143], v[208:211], v[76:79]
	v_mfma_f32_16x16x32_bf16 v[72:75], v[158:161], v[208:211], v[72:75]
	v_mfma_f32_16x16x32_bf16 v[124:127], v[144:147], v[186:189], v[124:127]
	v_mfma_f32_16x16x32_bf16 v[120:123], v[162:165], v[186:189], v[120:123]
	v_mfma_f32_16x16x32_bf16 v[108:111], v[144:147], v[194:197], v[108:111]
	v_mfma_f32_16x16x32_bf16 v[104:107], v[162:165], v[194:197], v[104:107]
	v_mfma_f32_16x16x32_bf16 v[92:95], v[144:147], v[202:205], v[92:95]
	v_mfma_f32_16x16x32_bf16 v[88:91], v[162:165], v[202:205], v[88:91]
	v_mfma_f32_16x16x32_bf16 v[76:79], v[144:147], v[212:215], v[76:79]
	v_mfma_f32_16x16x32_bf16 v[72:75], v[162:165], v[212:215], v[72:75]
	v_mfma_f32_16x16x32_bf16 v[116:119], v[166:169], v[182:185], v[116:119]
	v_mfma_f32_16x16x32_bf16 v[112:115], v[174:177], v[182:185], v[112:115]
	v_mfma_f32_16x16x32_bf16 v[100:103], v[166:169], v[190:193], v[100:103]
	v_mfma_f32_16x16x32_bf16 v[96:99], v[174:177], v[190:193], v[96:99]
	v_mfma_f32_16x16x32_bf16 v[84:87], v[166:169], v[198:201], v[84:87]
	v_mfma_f32_16x16x32_bf16 v[80:83], v[174:177], v[198:201], v[80:83]
	v_mfma_f32_16x16x32_bf16 v[68:71], v[166:169], v[208:211], v[68:71]
	v_mfma_f32_16x16x32_bf16 v[64:67], v[174:177], v[208:211], v[64:67]
	v_mfma_f32_16x16x32_bf16 v[116:119], v[170:173], v[186:189], v[116:119]
	v_mfma_f32_16x16x32_bf16 v[112:115], v[178:181], v[186:189], v[112:115]
	v_mfma_f32_16x16x32_bf16 v[100:103], v[170:173], v[194:197], v[100:103]
	v_mfma_f32_16x16x32_bf16 v[96:99], v[178:181], v[194:197], v[96:99]
	v_mfma_f32_16x16x32_bf16 v[84:87], v[170:173], v[202:205], v[84:87]
	v_mfma_f32_16x16x32_bf16 v[80:83], v[178:181], v[202:205], v[80:83]
	v_mfma_f32_16x16x32_bf16 v[68:71], v[170:173], v[212:215], v[68:71]
	v_mfma_f32_16x16x32_bf16 v[64:67], v[178:181], v[212:215], v[64:67]
	s_barrier
	s_add_i32 s62, s54, s45
	s_mov_b32 m0, s62
	s_nop 0
	global_load_lds_dwordx4 v128, s[38:39]
	s_add_i32 m0, s62, 0x2000
	s_add_u32 s62, s38, 0x40000
	s_mov_b64 s[98:99], s[38:39]
	s_addc_u32 s63, s39, 0
	s_add_i32 s64, s55, s45
	global_load_lds_dwordx4 v130, s[38:39]
	s_mov_b32 m0, s64
	s_mov_b64 s[100:101], s[40:41]
	global_load_lds_dwordx4 v128, s[62:63]
	s_add_i32 m0, s64, 0x2000
	s_nop 0
	global_load_lds_dwordx4 v130, s[62:63]
	ds_read_b128 v[182:185], v155 offset:16384
	ds_read_b128 v[186:189], v155 offset:17408
	ds_read_b128 v[190:193], v155 offset:18432
	ds_read_b128 v[194:197], v155 offset:19456
	ds_read_b128 v[198:201], v155 offset:20480
	ds_read_b128 v[202:205], v155 offset:21504
	ds_read_b128 v[208:211], v155 offset:22528
	ds_read_b128 v[212:215], v155 offset:23552
	s_waitcnt vmcnt(6)
	s_waitcnt lgkmcnt(0)
	s_barrier
	s_waitcnt lgkmcnt(0)
	v_mfma_f32_16x16x32_bf16 v[60:63], v[140:143], v[182:185], v[60:63]
	v_mfma_f32_16x16x32_bf16 v[56:59], v[158:161], v[182:185], v[56:59]
	v_mfma_f32_16x16x32_bf16 v[44:47], v[140:143], v[190:193], v[44:47]
	v_mfma_f32_16x16x32_bf16 v[40:43], v[158:161], v[190:193], v[40:43]
	v_mfma_f32_16x16x32_bf16 v[28:31], v[140:143], v[198:201], v[28:31]
	v_mfma_f32_16x16x32_bf16 v[24:27], v[158:161], v[198:201], v[24:27]
	v_mfma_f32_16x16x32_bf16 v[12:15], v[140:143], v[208:211], v[12:15]
	v_mfma_f32_16x16x32_bf16 v[8:11], v[158:161], v[208:211], v[8:11]
	v_mfma_f32_16x16x32_bf16 v[60:63], v[144:147], v[186:189], v[60:63]
	v_mfma_f32_16x16x32_bf16 v[56:59], v[162:165], v[186:189], v[56:59]
	v_mfma_f32_16x16x32_bf16 v[44:47], v[144:147], v[194:197], v[44:47]
	v_mfma_f32_16x16x32_bf16 v[40:43], v[162:165], v[194:197], v[40:43]
	v_mfma_f32_16x16x32_bf16 v[28:31], v[144:147], v[202:205], v[28:31]
	v_mfma_f32_16x16x32_bf16 v[24:27], v[162:165], v[202:205], v[24:27]
	v_mfma_f32_16x16x32_bf16 v[12:15], v[144:147], v[212:215], v[12:15]
	v_mfma_f32_16x16x32_bf16 v[8:11], v[162:165], v[212:215], v[8:11]
	v_mfma_f32_16x16x32_bf16 v[52:55], v[166:169], v[182:185], v[52:55]
	v_mfma_f32_16x16x32_bf16 v[48:51], v[174:177], v[182:185], v[48:51]
	v_mfma_f32_16x16x32_bf16 v[36:39], v[166:169], v[190:193], v[36:39]
	v_mfma_f32_16x16x32_bf16 v[32:35], v[174:177], v[190:193], v[32:35]
	v_mfma_f32_16x16x32_bf16 v[20:23], v[166:169], v[198:201], v[20:23]
	v_mfma_f32_16x16x32_bf16 v[16:19], v[174:177], v[198:201], v[16:19]
	v_mfma_f32_16x16x32_bf16 v[4:7], v[166:169], v[208:211], v[4:7]
	v_mfma_f32_16x16x32_bf16 v[0:3], v[174:177], v[208:211], v[0:3]
	v_mfma_f32_16x16x32_bf16 v[52:55], v[170:173], v[186:189], v[52:55]
	v_mfma_f32_16x16x32_bf16 v[48:51], v[178:181], v[186:189], v[48:51]
	v_mfma_f32_16x16x32_bf16 v[36:39], v[170:173], v[194:197], v[36:39]
	v_mfma_f32_16x16x32_bf16 v[32:35], v[178:181], v[194:197], v[32:35]
	v_mfma_f32_16x16x32_bf16 v[20:23], v[170:173], v[202:205], v[20:23]
	v_mfma_f32_16x16x32_bf16 v[16:19], v[178:181], v[202:205], v[16:19]
	v_mfma_f32_16x16x32_bf16 v[4:7], v[170:173], v[212:215], v[4:7]
	v_mfma_f32_16x16x32_bf16 v[0:3], v[178:181], v[212:215], v[0:3]
	s_barrier
	s_mov_b32 m0, s46
	s_nop 0
	global_load_lds_dwordx4 v128, s[40:41]
	s_mov_b32 m0, s47
	s_nop 0
	global_load_lds_dwordx4 v130, s[40:41]
	s_add_i32 s62, 0, 0x18000
	v_add_u32_e32 v157, s62, v151
	s_add_i32 s63, 0, 0x1c000
	ds_read_b128 v[140:143], v157
	ds_read_b128 v[144:147], v157 offset:1024
	ds_read_b128 v[158:161], v157 offset:2048
	ds_read_b128 v[162:165], v157 offset:3072
	v_add_u32_e32 v157, s63, v151
	ds_read_b128 v[166:169], v157
	ds_read_b128 v[170:173], v157 offset:1024
	ds_read_b128 v[174:177], v157 offset:2048
	ds_read_b128 v[178:181], v157 offset:3072
	s_add_u32 s40, s40, 0x40000
	s_addc_u32 s41, s41, 0
	s_mov_b32 m0, s48
	ds_read_b128 v[182:185], v155 offset:32768
	ds_read_b128 v[186:189], v155 offset:33792
	ds_read_b128 v[190:193], v155 offset:34816
	ds_read_b128 v[194:197], v155 offset:35840
	ds_read_b128 v[198:201], v155 offset:36864
	ds_read_b128 v[202:205], v155 offset:37888
	ds_read_b128 v[208:211], v155 offset:38912
	ds_read_b128 v[212:215], v155 offset:39936
	global_load_lds_dwordx4 v128, s[40:41]
	s_mov_b32 m0, s49
	s_nop 0
	global_load_lds_dwordx4 v130, s[40:41]
	s_waitcnt vmcnt(8)
	s_waitcnt lgkmcnt(0)
	s_barrier
	s_waitcnt lgkmcnt(0)
	v_mfma_f32_16x16x32_bf16 v[124:127], v[140:143], v[182:185], v[124:127]
	v_mfma_f32_16x16x32_bf16 v[120:123], v[158:161], v[182:185], v[120:123]
	v_mfma_f32_16x16x32_bf16 v[108:111], v[140:143], v[190:193], v[108:111]
	v_mfma_f32_16x16x32_bf16 v[104:107], v[158:161], v[190:193], v[104:107]
	v_mfma_f32_16x16x32_bf16 v[92:95], v[140:143], v[198:201], v[92:95]
	v_mfma_f32_16x16x32_bf16 v[88:91], v[158:161], v[198:201], v[88:91]
	v_mfma_f32_16x16x32_bf16 v[76:79], v[140:143], v[208:211], v[76:79]
	v_mfma_f32_16x16x32_bf16 v[72:75], v[158:161], v[208:211], v[72:75]
	v_mfma_f32_16x16x32_bf16 v[124:127], v[144:147], v[186:189], v[124:127]
	v_mfma_f32_16x16x32_bf16 v[120:123], v[162:165], v[186:189], v[120:123]
	v_mfma_f32_16x16x32_bf16 v[108:111], v[144:147], v[194:197], v[108:111]
	v_mfma_f32_16x16x32_bf16 v[104:107], v[162:165], v[194:197], v[104:107]
	v_mfma_f32_16x16x32_bf16 v[92:95], v[144:147], v[202:205], v[92:95]
	v_mfma_f32_16x16x32_bf16 v[88:91], v[162:165], v[202:205], v[88:91]
	v_mfma_f32_16x16x32_bf16 v[76:79], v[144:147], v[212:215], v[76:79]
	v_mfma_f32_16x16x32_bf16 v[72:75], v[162:165], v[212:215], v[72:75]
	v_mfma_f32_16x16x32_bf16 v[116:119], v[166:169], v[182:185], v[116:119]
	v_mfma_f32_16x16x32_bf16 v[112:115], v[174:177], v[182:185], v[112:115]
	v_mfma_f32_16x16x32_bf16 v[100:103], v[166:169], v[190:193], v[100:103]
	v_mfma_f32_16x16x32_bf16 v[96:99], v[174:177], v[190:193], v[96:99]
	v_mfma_f32_16x16x32_bf16 v[84:87], v[166:169], v[198:201], v[84:87]
	v_mfma_f32_16x16x32_bf16 v[80:83], v[174:177], v[198:201], v[80:83]
	v_mfma_f32_16x16x32_bf16 v[68:71], v[166:169], v[208:211], v[68:71]
	v_mfma_f32_16x16x32_bf16 v[64:67], v[174:177], v[208:211], v[64:67]
	v_mfma_f32_16x16x32_bf16 v[116:119], v[170:173], v[186:189], v[116:119]
	v_mfma_f32_16x16x32_bf16 v[112:115], v[178:181], v[186:189], v[112:115]
	v_mfma_f32_16x16x32_bf16 v[100:103], v[170:173], v[194:197], v[100:103]
	v_mfma_f32_16x16x32_bf16 v[96:99], v[178:181], v[194:197], v[96:99]
	v_mfma_f32_16x16x32_bf16 v[84:87], v[170:173], v[202:205], v[84:87]
	v_mfma_f32_16x16x32_bf16 v[80:83], v[178:181], v[202:205], v[80:83]
	v_mfma_f32_16x16x32_bf16 v[68:71], v[170:173], v[212:215], v[68:71]
	v_mfma_f32_16x16x32_bf16 v[64:67], v[178:181], v[212:215], v[64:67]
	s_barrier
	s_add_i32 s40, s62, s45
	s_mov_b32 m0, s40
	s_nop 0
	global_load_lds_dwordx4 v148, s[38:39]
	s_add_i32 m0, s40, 0x2000
	s_add_u32 s38, s38, 0x40080
	s_addc_u32 s39, s39, 0
	s_add_i32 s40, s63, s45
	global_load_lds_dwordx4 v149, s[98:99]
	s_mov_b32 m0, s40
	s_nop 0
	global_load_lds_dwordx4 v128, s[38:39]
	s_add_i32 m0, s40, 0x2000
	s_nop 0
	global_load_lds_dwordx4 v130, s[38:39]
	s_cmp_lg_u32 s61, 12
	s_cbranch_scc1 .Lbal_last_17
	s_mov_b32 m0, s51
	s_nop 0
	global_load_lds_dwordx4 v148, s[100:101]
	s_mov_b32 m0, s52
	s_nop 0
	global_load_lds_dwordx4 v149, s[100:101]

.Lbal_first_16:
	ds_read_b128 v[144:147], v151
	ds_read_b128 v[156:159], v151 offset:1024
	ds_read_b128 v[160:163], v151 offset:2048
	ds_read_b128 v[164:167], v151 offset:3072
	ds_read_b128 v[168:171], v152
	ds_read_b128 v[172:175], v152 offset:1024
	ds_read_b128 v[176:179], v152 offset:2048
	ds_read_b128 v[180:183], v152 offset:3072
	s_add_u32 s26, s6, 0xfffc0080
	s_addc_u32 s27, s7, -1
	s_cmp_eq_u32 s53, 12
	s_cselect_b32 s29, s19, s27
	s_cselect_b32 s28, s49, s26
	s_cselect_b32 s27, s17, s52
	s_cselect_b32 s26, s50, s51
	s_add_i32 m0, s25, 0xc000
	ds_read_b128 v[184:187], v153
	ds_read_b128 v[188:191], v153 offset:1024
	ds_read_b128 v[192:195], v153 offset:2048
	ds_read_b128 v[196:199], v153 offset:3072
	ds_read_b128 v[200:203], v153 offset:4096
	ds_read_b128 v[208:211], v153 offset:5120
	ds_read_b128 v[212:215], v153 offset:6144
	ds_read_b128 v[216:219], v153 offset:7168
	global_load_lds_dwordx4 v138, s[6:7]
	s_add_i32 m0, s25, 0xe000
	s_nop 0
	global_load_lds_dwordx4 v136, s[6:7]
	s_waitcnt vmcnt(8)
	s_waitcnt lgkmcnt(0)
	s_barrier
	s_waitcnt lgkmcnt(0)
	v_mfma_f32_16x16x32_bf16 v[124:127], v[144:147], v[184:187], v[124:127]
	v_mfma_f32_16x16x32_bf16 v[120:123], v[160:163], v[184:187], v[120:123]
	v_mfma_f32_16x16x32_bf16 v[108:111], v[144:147], v[192:195], v[108:111]
	v_mfma_f32_16x16x32_bf16 v[104:107], v[160:163], v[192:195], v[104:107]
	v_mfma_f32_16x16x32_bf16 v[92:95], v[144:147], v[200:203], v[92:95]
	v_mfma_f32_16x16x32_bf16 v[88:91], v[160:163], v[200:203], v[88:91]
	v_mfma_f32_16x16x32_bf16 v[76:79], v[144:147], v[212:215], v[76:79]
	v_mfma_f32_16x16x32_bf16 v[72:75], v[160:163], v[212:215], v[72:75]
	v_mfma_f32_16x16x32_bf16 v[124:127], v[156:159], v[188:191], v[124:127]
	v_mfma_f32_16x16x32_bf16 v[120:123], v[164:167], v[188:191], v[120:123]
	v_mfma_f32_16x16x32_bf16 v[108:111], v[156:159], v[196:199], v[108:111]
	v_mfma_f32_16x16x32_bf16 v[104:107], v[164:167], v[196:199], v[104:107]
	v_mfma_f32_16x16x32_bf16 v[92:95], v[156:159], v[208:211], v[92:95]
	v_mfma_f32_16x16x32_bf16 v[88:91], v[164:167], v[208:211], v[88:91]
	v_mfma_f32_16x16x32_bf16 v[76:79], v[156:159], v[216:219], v[76:79]
	v_mfma_f32_16x16x32_bf16 v[72:75], v[164:167], v[216:219], v[72:75]
	v_mfma_f32_16x16x32_bf16 v[116:119], v[168:171], v[184:187], v[116:119]
	v_mfma_f32_16x16x32_bf16 v[112:115], v[176:179], v[184:187], v[112:115]
	v_mfma_f32_16x16x32_bf16 v[100:103], v[168:171], v[192:195], v[100:103]
	v_mfma_f32_16x16x32_bf16 v[96:99], v[176:179], v[192:195], v[96:99]
	v_mfma_f32_16x16x32_bf16 v[84:87], v[168:171], v[200:203], v[84:87]
	v_mfma_f32_16x16x32_bf16 v[80:83], v[176:179], v[200:203], v[80:83]
	v_mfma_f32_16x16x32_bf16 v[68:71], v[168:171], v[212:215], v[68:71]
	v_mfma_f32_16x16x32_bf16 v[64:67], v[176:179], v[212:215], v[64:67]
	v_mfma_f32_16x16x32_bf16 v[116:119], v[172:175], v[188:191], v[116:119]
	v_mfma_f32_16x16x32_bf16 v[112:115], v[180:183], v[188:191], v[112:115]
	v_mfma_f32_16x16x32_bf16 v[100:103], v[172:175], v[196:199], v[100:103]
	v_mfma_f32_16x16x32_bf16 v[96:99], v[180:183], v[196:199], v[96:99]
	v_mfma_f32_16x16x32_bf16 v[84:87], v[172:175], v[208:211], v[84:87]
	v_mfma_f32_16x16x32_bf16 v[80:83], v[180:183], v[208:211], v[80:83]
	v_mfma_f32_16x16x32_bf16 v[68:71], v[172:175], v[216:219], v[68:71]
	v_mfma_f32_16x16x32_bf16 v[64:67], v[180:183], v[216:219], v[64:67]
	s_barrier
	s_add_i32 s54, s45, s38
	s_mov_b32 m0, s54
	s_nop 0
	global_load_lds_dwordx4 v130, s[26:27]
	s_add_i32 m0, s54, 0x2000
	s_add_u32 s54, s26, 0x40000
	s_mov_b64 s[98:99], s[26:27]
	s_addc_u32 s55, s27, 0
	s_add_i32 s56, s46, s38
	global_load_lds_dwordx4 v134, s[26:27]
	s_mov_b32 m0, s56
	s_mov_b64 s[100:101], s[28:29]
	global_load_lds_dwordx4 v130, s[54:55]
	s_add_i32 m0, s56, 0x2000
	s_nop 0
	global_load_lds_dwordx4 v134, s[54:55]
	ds_read_b128 v[184:187], v153 offset:16384
	ds_read_b128 v[188:191], v153 offset:17408
	ds_read_b128 v[192:195], v153 offset:18432
	ds_read_b128 v[196:199], v153 offset:19456
	ds_read_b128 v[200:203], v153 offset:20480
	ds_read_b128 v[208:211], v153 offset:21504
	ds_read_b128 v[212:215], v153 offset:22528
	ds_read_b128 v[216:219], v153 offset:23552
	s_waitcnt vmcnt(6)
	s_waitcnt lgkmcnt(0)
	s_barrier
	s_waitcnt lgkmcnt(0)
	v_mfma_f32_16x16x32_bf16 v[60:63], v[144:147], v[184:187], v[60:63]
	v_mfma_f32_16x16x32_bf16 v[56:59], v[160:163], v[184:187], v[56:59]
	v_mfma_f32_16x16x32_bf16 v[44:47], v[144:147], v[192:195], v[44:47]
	v_mfma_f32_16x16x32_bf16 v[40:43], v[160:163], v[192:195], v[40:43]
	v_mfma_f32_16x16x32_bf16 v[28:31], v[144:147], v[200:203], v[28:31]
	v_mfma_f32_16x16x32_bf16 v[24:27], v[160:163], v[200:203], v[24:27]
	v_mfma_f32_16x16x32_bf16 v[12:15], v[144:147], v[212:215], v[12:15]
	v_mfma_f32_16x16x32_bf16 v[8:11], v[160:163], v[212:215], v[8:11]
	v_mfma_f32_16x16x32_bf16 v[60:63], v[156:159], v[188:191], v[60:63]
	v_mfma_f32_16x16x32_bf16 v[56:59], v[164:167], v[188:191], v[56:59]
	v_mfma_f32_16x16x32_bf16 v[44:47], v[156:159], v[196:199], v[44:47]
	v_mfma_f32_16x16x32_bf16 v[40:43], v[164:167], v[196:199], v[40:43]
	v_mfma_f32_16x16x32_bf16 v[28:31], v[156:159], v[208:211], v[28:31]
	v_mfma_f32_16x16x32_bf16 v[24:27], v[164:167], v[208:211], v[24:27]
	v_mfma_f32_16x16x32_bf16 v[12:15], v[156:159], v[216:219], v[12:15]
	v_mfma_f32_16x16x32_bf16 v[8:11], v[164:167], v[216:219], v[8:11]
	v_mfma_f32_16x16x32_bf16 v[52:55], v[168:171], v[184:187], v[52:55]
	v_mfma_f32_16x16x32_bf16 v[48:51], v[176:179], v[184:187], v[48:51]
	v_mfma_f32_16x16x32_bf16 v[36:39], v[168:171], v[192:195], v[36:39]
	v_mfma_f32_16x16x32_bf16 v[32:35], v[176:179], v[192:195], v[32:35]
	v_mfma_f32_16x16x32_bf16 v[20:23], v[168:171], v[200:203], v[20:23]
	v_mfma_f32_16x16x32_bf16 v[16:19], v[176:179], v[200:203], v[16:19]
	v_mfma_f32_16x16x32_bf16 v[4:7], v[168:171], v[212:215], v[4:7]
	v_mfma_f32_16x16x32_bf16 v[0:3], v[176:179], v[212:215], v[0:3]
	v_mfma_f32_16x16x32_bf16 v[52:55], v[172:175], v[188:191], v[52:55]
	v_mfma_f32_16x16x32_bf16 v[48:51], v[180:183], v[188:191], v[48:51]
	v_mfma_f32_16x16x32_bf16 v[36:39], v[172:175], v[196:199], v[36:39]
	v_mfma_f32_16x16x32_bf16 v[32:35], v[180:183], v[196:199], v[32:35]
	v_mfma_f32_16x16x32_bf16 v[20:23], v[172:175], v[208:211], v[20:23]
	v_mfma_f32_16x16x32_bf16 v[16:19], v[180:183], v[208:211], v[16:19]
	v_mfma_f32_16x16x32_bf16 v[4:7], v[172:175], v[216:219], v[4:7]
	v_mfma_f32_16x16x32_bf16 v[0:3], v[180:183], v[216:219], v[0:3]
	s_barrier
	s_mov_b32 m0, s25
	s_nop 0
	global_load_lds_dwordx4 v128, s[28:29]
	s_mov_b32 m0, s39
	s_nop 0
	global_load_lds_dwordx4 v132, s[28:29]
	s_add_i32 s54, 0, 0x18000
	v_add_u32_e32 v155, s54, v149
	s_add_i32 s55, 0, 0x1c000
	ds_read_b128 v[144:147], v155
	ds_read_b128 v[156:159], v155 offset:1024
	ds_read_b128 v[160:163], v155 offset:2048
	ds_read_b128 v[164:167], v155 offset:3072
	v_add_u32_e32 v155, s55, v149
	ds_read_b128 v[168:171], v155
	ds_read_b128 v[172:175], v155 offset:1024
	ds_read_b128 v[176:179], v155 offset:2048
	ds_read_b128 v[180:183], v155 offset:3072
	s_add_u32 s28, s28, 0x40000
	s_addc_u32 s29, s29, 0
	s_mov_b32 m0, s40
	ds_read_b128 v[184:187], v153 offset:32768
	ds_read_b128 v[188:191], v153 offset:33792
	ds_read_b128 v[192:195], v153 offset:34816
	ds_read_b128 v[196:199], v153 offset:35840
	ds_read_b128 v[200:203], v153 offset:36864
	ds_read_b128 v[208:211], v153 offset:37888
	ds_read_b128 v[212:215], v153 offset:38912
	ds_read_b128 v[216:219], v153 offset:39936
	global_load_lds_dwordx4 v128, s[28:29]
	s_mov_b32 m0, s41
	s_nop 0
	global_load_lds_dwordx4 v132, s[28:29]
	s_waitcnt vmcnt(8)
	s_waitcnt lgkmcnt(0)
	s_barrier
	s_waitcnt lgkmcnt(0)
	v_mfma_f32_16x16x32_bf16 v[124:127], v[144:147], v[184:187], v[124:127]
	v_mfma_f32_16x16x32_bf16 v[120:123], v[160:163], v[184:187], v[120:123]
	v_mfma_f32_16x16x32_bf16 v[108:111], v[144:147], v[192:195], v[108:111]
	v_mfma_f32_16x16x32_bf16 v[104:107], v[160:163], v[192:195], v[104:107]
	v_mfma_f32_16x16x32_bf16 v[92:95], v[144:147], v[200:203], v[92:95]
	v_mfma_f32_16x16x32_bf16 v[88:91], v[160:163], v[200:203], v[88:91]
	v_mfma_f32_16x16x32_bf16 v[76:79], v[144:147], v[212:215], v[76:79]
	v_mfma_f32_16x16x32_bf16 v[72:75], v[160:163], v[212:215], v[72:75]
	v_mfma_f32_16x16x32_bf16 v[124:127], v[156:159], v[188:191], v[124:127]
	v_mfma_f32_16x16x32_bf16 v[120:123], v[164:167], v[188:191], v[120:123]
	v_mfma_f32_16x16x32_bf16 v[108:111], v[156:159], v[196:199], v[108:111]
	v_mfma_f32_16x16x32_bf16 v[104:107], v[164:167], v[196:199], v[104:107]
	v_mfma_f32_16x16x32_bf16 v[92:95], v[156:159], v[208:211], v[92:95]
	v_mfma_f32_16x16x32_bf16 v[88:91], v[164:167], v[208:211], v[88:91]
	v_mfma_f32_16x16x32_bf16 v[76:79], v[156:159], v[216:219], v[76:79]
	v_mfma_f32_16x16x32_bf16 v[72:75], v[164:167], v[216:219], v[72:75]
	v_mfma_f32_16x16x32_bf16 v[116:119], v[168:171], v[184:187], v[116:119]
	v_mfma_f32_16x16x32_bf16 v[112:115], v[176:179], v[184:187], v[112:115]
	v_mfma_f32_16x16x32_bf16 v[100:103], v[168:171], v[192:195], v[100:103]
	v_mfma_f32_16x16x32_bf16 v[96:99], v[176:179], v[192:195], v[96:99]
	v_mfma_f32_16x16x32_bf16 v[84:87], v[168:171], v[200:203], v[84:87]
	v_mfma_f32_16x16x32_bf16 v[80:83], v[176:179], v[200:203], v[80:83]
	v_mfma_f32_16x16x32_bf16 v[68:71], v[168:171], v[212:215], v[68:71]
	v_mfma_f32_16x16x32_bf16 v[64:67], v[176:179], v[212:215], v[64:67]
	v_mfma_f32_16x16x32_bf16 v[116:119], v[172:175], v[188:191], v[116:119]
	v_mfma_f32_16x16x32_bf16 v[112:115], v[180:183], v[188:191], v[112:115]
	v_mfma_f32_16x16x32_bf16 v[100:103], v[172:175], v[196:199], v[100:103]
	v_mfma_f32_16x16x32_bf16 v[96:99], v[180:183], v[196:199], v[96:99]
	v_mfma_f32_16x16x32_bf16 v[84:87], v[172:175], v[208:211], v[84:87]
	v_mfma_f32_16x16x32_bf16 v[80:83], v[180:183], v[208:211], v[80:83]
	v_mfma_f32_16x16x32_bf16 v[68:71], v[172:175], v[216:219], v[68:71]
	v_mfma_f32_16x16x32_bf16 v[64:67], v[180:183], v[216:219], v[64:67]
	s_barrier
	s_add_i32 s28, s54, s38
	s_mov_b32 m0, s28
	s_nop 0
	global_load_lds_dwordx4 v205, s[26:27]
	s_add_i32 m0, s28, 0x2000
	s_add_u32 s26, s26, 0x40080
	s_addc_u32 s27, s27, 0
	s_add_i32 s28, s55, s38
	global_load_lds_dwordx4 v221, s[98:99]
	s_mov_b32 m0, s28
	s_nop 0
	global_load_lds_dwordx4 v130, s[26:27]
	s_add_i32 m0, s28, 0x2000
	s_nop 0
	global_load_lds_dwordx4 v134, s[26:27]
	s_cmp_lg_u32 s53, 12
	s_cbranch_scc1 .Lbal_last_16
	s_mov_b32 m0, s43
	s_nop 0
	global_load_lds_dwordx4 v204, s[100:101]
	s_mov_b32 m0, s44
	s_nop 0
	global_load_lds_dwordx4 v220, s[100:101]

.Lbal_first_15:
	ds_read_b128 v[144:147], v151
	ds_read_b128 v[154:157], v151 offset:1024
	ds_read_b128 v[158:161], v151 offset:2048
	ds_read_b128 v[162:165], v151 offset:3072
	ds_read_b128 v[166:169], v152
	ds_read_b128 v[170:173], v152 offset:1024
	ds_read_b128 v[174:177], v152 offset:2048
	ds_read_b128 v[178:181], v152 offset:3072
	s_add_u32 s26, s24, 0xfffe0080
	s_addc_u32 s27, s25, -1
	s_cmp_eq_u32 s50, 4
	s_cselect_b32 s29, s17, s27
	s_cselect_b32 s28, s46, s26
	s_cselect_b32 s27, s15, s49
	s_cselect_b32 s26, s47, s48
	s_add_i32 m0, s23, 0xc000
	ds_read_b128 v[182:185], v153
	ds_read_b128 v[186:189], v153 offset:1024
	ds_read_b128 v[190:193], v153 offset:2048
	ds_read_b128 v[194:197], v153 offset:3072
	ds_read_b128 v[198:201], v153 offset:4096
	ds_read_b128 v[202:205], v153 offset:5120
	ds_read_b128 v[208:211], v153 offset:6144
	ds_read_b128 v[212:215], v153 offset:7168
	global_load_lds_dwordx4 v138, s[24:25]
	s_add_i32 m0, s23, 0xe000
	s_nop 0
	global_load_lds_dwordx4 v136, s[24:25]
	s_waitcnt vmcnt(8)
	s_waitcnt lgkmcnt(0)
	s_barrier
	s_waitcnt lgkmcnt(0)
	v_mfma_f32_16x16x32_bf16 v[124:127], v[144:147], v[182:185], v[124:127]
	v_mfma_f32_16x16x32_bf16 v[120:123], v[158:161], v[182:185], v[120:123]
	v_mfma_f32_16x16x32_bf16 v[108:111], v[144:147], v[190:193], v[108:111]
	v_mfma_f32_16x16x32_bf16 v[104:107], v[158:161], v[190:193], v[104:107]
	v_mfma_f32_16x16x32_bf16 v[92:95], v[144:147], v[198:201], v[92:95]
	v_mfma_f32_16x16x32_bf16 v[88:91], v[158:161], v[198:201], v[88:91]
	v_mfma_f32_16x16x32_bf16 v[76:79], v[144:147], v[208:211], v[76:79]
	v_mfma_f32_16x16x32_bf16 v[72:75], v[158:161], v[208:211], v[72:75]
	v_mfma_f32_16x16x32_bf16 v[124:127], v[154:157], v[186:189], v[124:127]
	v_mfma_f32_16x16x32_bf16 v[120:123], v[162:165], v[186:189], v[120:123]
	v_mfma_f32_16x16x32_bf16 v[108:111], v[154:157], v[194:197], v[108:111]
	v_mfma_f32_16x16x32_bf16 v[104:107], v[162:165], v[194:197], v[104:107]
	v_mfma_f32_16x16x32_bf16 v[92:95], v[154:157], v[202:205], v[92:95]
	v_mfma_f32_16x16x32_bf16 v[88:91], v[162:165], v[202:205], v[88:91]
	v_mfma_f32_16x16x32_bf16 v[76:79], v[154:157], v[212:215], v[76:79]
	v_mfma_f32_16x16x32_bf16 v[72:75], v[162:165], v[212:215], v[72:75]
	v_mfma_f32_16x16x32_bf16 v[116:119], v[166:169], v[182:185], v[116:119]
	v_mfma_f32_16x16x32_bf16 v[112:115], v[174:177], v[182:185], v[112:115]
	v_mfma_f32_16x16x32_bf16 v[100:103], v[166:169], v[190:193], v[100:103]
	v_mfma_f32_16x16x32_bf16 v[96:99], v[174:177], v[190:193], v[96:99]
	v_mfma_f32_16x16x32_bf16 v[84:87], v[166:169], v[198:201], v[84:87]
	v_mfma_f32_16x16x32_bf16 v[80:83], v[174:177], v[198:201], v[80:83]
	v_mfma_f32_16x16x32_bf16 v[68:71], v[166:169], v[208:211], v[68:71]
	v_mfma_f32_16x16x32_bf16 v[64:67], v[174:177], v[208:211], v[64:67]
	v_mfma_f32_16x16x32_bf16 v[116:119], v[170:173], v[186:189], v[116:119]
	v_mfma_f32_16x16x32_bf16 v[112:115], v[178:181], v[186:189], v[112:115]
	v_mfma_f32_16x16x32_bf16 v[100:103], v[170:173], v[194:197], v[100:103]
	v_mfma_f32_16x16x32_bf16 v[96:99], v[178:181], v[194:197], v[96:99]
	v_mfma_f32_16x16x32_bf16 v[84:87], v[170:173], v[202:205], v[84:87]
	v_mfma_f32_16x16x32_bf16 v[80:83], v[178:181], v[202:205], v[80:83]
	v_mfma_f32_16x16x32_bf16 v[68:71], v[170:173], v[212:215], v[68:71]
	v_mfma_f32_16x16x32_bf16 v[64:67], v[178:181], v[212:215], v[64:67]
	s_barrier
	s_add_i32 s51, s43, s36
	s_mov_b32 m0, s51
	s_nop 0
	global_load_lds_dwordx4 v130, s[26:27]
	s_add_i32 m0, s51, 0x2000
	s_add_u32 s52, s26, 0x20000
	s_mov_b64 s[98:99], s[26:27]
	s_addc_u32 s53, s27, 0
	s_add_i32 s51, s44, s36
	global_load_lds_dwordx4 v134, s[26:27]
	s_mov_b32 m0, s51
	s_mov_b64 s[100:101], s[28:29]
	global_load_lds_dwordx4 v130, s[52:53]
	s_add_i32 m0, s51, 0x2000
	s_nop 0
	global_load_lds_dwordx4 v134, s[52:53]
	ds_read_b128 v[182:185], v153 offset:16384
	ds_read_b128 v[186:189], v153 offset:17408
	ds_read_b128 v[190:193], v153 offset:18432
	ds_read_b128 v[194:197], v153 offset:19456
	ds_read_b128 v[198:201], v153 offset:20480
	ds_read_b128 v[202:205], v153 offset:21504
	ds_read_b128 v[208:211], v153 offset:22528
	ds_read_b128 v[212:215], v153 offset:23552
	s_waitcnt vmcnt(6)
	s_waitcnt lgkmcnt(0)
	s_barrier
	s_waitcnt lgkmcnt(0)
	v_mfma_f32_16x16x32_bf16 v[60:63], v[144:147], v[182:185], v[60:63]
	v_mfma_f32_16x16x32_bf16 v[56:59], v[158:161], v[182:185], v[56:59]
	v_mfma_f32_16x16x32_bf16 v[44:47], v[144:147], v[190:193], v[44:47]
	v_mfma_f32_16x16x32_bf16 v[40:43], v[158:161], v[190:193], v[40:43]
	v_mfma_f32_16x16x32_bf16 v[28:31], v[144:147], v[198:201], v[28:31]
	v_mfma_f32_16x16x32_bf16 v[24:27], v[158:161], v[198:201], v[24:27]
	v_mfma_f32_16x16x32_bf16 v[12:15], v[144:147], v[208:211], v[12:15]
	v_mfma_f32_16x16x32_bf16 v[8:11], v[158:161], v[208:211], v[8:11]
	v_mfma_f32_16x16x32_bf16 v[60:63], v[154:157], v[186:189], v[60:63]
	v_mfma_f32_16x16x32_bf16 v[56:59], v[162:165], v[186:189], v[56:59]
	v_mfma_f32_16x16x32_bf16 v[44:47], v[154:157], v[194:197], v[44:47]
	v_mfma_f32_16x16x32_bf16 v[40:43], v[162:165], v[194:197], v[40:43]
	v_mfma_f32_16x16x32_bf16 v[28:31], v[154:157], v[202:205], v[28:31]
	v_mfma_f32_16x16x32_bf16 v[24:27], v[162:165], v[202:205], v[24:27]
	v_mfma_f32_16x16x32_bf16 v[12:15], v[154:157], v[212:215], v[12:15]
	v_mfma_f32_16x16x32_bf16 v[8:11], v[162:165], v[212:215], v[8:11]
	v_mfma_f32_16x16x32_bf16 v[52:55], v[166:169], v[182:185], v[52:55]
	v_mfma_f32_16x16x32_bf16 v[48:51], v[174:177], v[182:185], v[48:51]
	v_mfma_f32_16x16x32_bf16 v[36:39], v[166:169], v[190:193], v[36:39]
	v_mfma_f32_16x16x32_bf16 v[32:35], v[174:177], v[190:193], v[32:35]
	v_mfma_f32_16x16x32_bf16 v[20:23], v[166:169], v[198:201], v[20:23]
	v_mfma_f32_16x16x32_bf16 v[16:19], v[174:177], v[198:201], v[16:19]
	v_mfma_f32_16x16x32_bf16 v[4:7], v[166:169], v[208:211], v[4:7]
	v_mfma_f32_16x16x32_bf16 v[0:3], v[174:177], v[208:211], v[0:3]
	v_mfma_f32_16x16x32_bf16 v[52:55], v[170:173], v[186:189], v[52:55]
	v_mfma_f32_16x16x32_bf16 v[48:51], v[178:181], v[186:189], v[48:51]
	v_mfma_f32_16x16x32_bf16 v[36:39], v[170:173], v[194:197], v[36:39]
	v_mfma_f32_16x16x32_bf16 v[32:35], v[178:181], v[194:197], v[32:35]
	v_mfma_f32_16x16x32_bf16 v[20:23], v[170:173], v[202:205], v[20:23]
	v_mfma_f32_16x16x32_bf16 v[16:19], v[178:181], v[202:205], v[16:19]
	v_mfma_f32_16x16x32_bf16 v[4:7], v[170:173], v[212:215], v[4:7]
	v_mfma_f32_16x16x32_bf16 v[0:3], v[178:181], v[212:215], v[0:3]
	s_barrier
	s_mov_b32 m0, s23
	s_nop 0
	global_load_lds_dwordx4 v128, s[28:29]
	s_mov_b32 m0, s37
	s_nop 0
	global_load_lds_dwordx4 v132, s[28:29]
	s_add_i32 s51, 0, 0x18000
	s_add_i32 s52, 0, 0x1c000
	v_add_u32_e32 v162, s51, v149
	v_add_u32_e32 v178, s52, v149
	ds_read_b128 v[144:147], v162
	ds_read_b128 v[154:157], v162 offset:1024
	ds_read_b128 v[158:161], v162 offset:2048
	ds_read_b128 v[162:165], v162 offset:3072
	ds_read_b128 v[166:169], v178
	ds_read_b128 v[170:173], v178 offset:1024
	ds_read_b128 v[174:177], v178 offset:2048
	ds_read_b128 v[178:181], v178 offset:3072
	s_add_u32 s28, s28, 0x20000
	s_addc_u32 s29, s29, 0
	s_mov_b32 m0, s38
	ds_read_b128 v[182:185], v153 offset:32768
	ds_read_b128 v[186:189], v153 offset:33792
	ds_read_b128 v[190:193], v153 offset:34816
	ds_read_b128 v[194:197], v153 offset:35840
	ds_read_b128 v[198:201], v153 offset:36864
	ds_read_b128 v[202:205], v153 offset:37888
	ds_read_b128 v[208:211], v153 offset:38912
	ds_read_b128 v[212:215], v153 offset:39936
	global_load_lds_dwordx4 v128, s[28:29]
	s_mov_b32 m0, s39
	s_nop 0
	global_load_lds_dwordx4 v132, s[28:29]
	s_waitcnt vmcnt(8)
	s_waitcnt lgkmcnt(0)
	s_barrier
	s_waitcnt lgkmcnt(0)
	v_mfma_f32_16x16x32_bf16 v[124:127], v[144:147], v[182:185], v[124:127]
	v_mfma_f32_16x16x32_bf16 v[120:123], v[158:161], v[182:185], v[120:123]
	v_mfma_f32_16x16x32_bf16 v[108:111], v[144:147], v[190:193], v[108:111]
	v_mfma_f32_16x16x32_bf16 v[104:107], v[158:161], v[190:193], v[104:107]
	v_mfma_f32_16x16x32_bf16 v[92:95], v[144:147], v[198:201], v[92:95]
	v_mfma_f32_16x16x32_bf16 v[88:91], v[158:161], v[198:201], v[88:91]
	v_mfma_f32_16x16x32_bf16 v[76:79], v[144:147], v[208:211], v[76:79]
	v_mfma_f32_16x16x32_bf16 v[72:75], v[158:161], v[208:211], v[72:75]
	v_mfma_f32_16x16x32_bf16 v[124:127], v[154:157], v[186:189], v[124:127]
	v_mfma_f32_16x16x32_bf16 v[120:123], v[162:165], v[186:189], v[120:123]
	v_mfma_f32_16x16x32_bf16 v[108:111], v[154:157], v[194:197], v[108:111]
	v_mfma_f32_16x16x32_bf16 v[104:107], v[162:165], v[194:197], v[104:107]
	v_mfma_f32_16x16x32_bf16 v[92:95], v[154:157], v[202:205], v[92:95]
	v_mfma_f32_16x16x32_bf16 v[88:91], v[162:165], v[202:205], v[88:91]
	v_mfma_f32_16x16x32_bf16 v[76:79], v[154:157], v[212:215], v[76:79]
	v_mfma_f32_16x16x32_bf16 v[72:75], v[162:165], v[212:215], v[72:75]
	v_mfma_f32_16x16x32_bf16 v[116:119], v[166:169], v[182:185], v[116:119]
	v_mfma_f32_16x16x32_bf16 v[112:115], v[174:177], v[182:185], v[112:115]
	v_mfma_f32_16x16x32_bf16 v[100:103], v[166:169], v[190:193], v[100:103]
	v_mfma_f32_16x16x32_bf16 v[96:99], v[174:177], v[190:193], v[96:99]
	v_mfma_f32_16x16x32_bf16 v[84:87], v[166:169], v[198:201], v[84:87]
	v_mfma_f32_16x16x32_bf16 v[80:83], v[174:177], v[198:201], v[80:83]
	v_mfma_f32_16x16x32_bf16 v[68:71], v[166:169], v[208:211], v[68:71]
	v_mfma_f32_16x16x32_bf16 v[64:67], v[174:177], v[208:211], v[64:67]
	v_mfma_f32_16x16x32_bf16 v[116:119], v[170:173], v[186:189], v[116:119]
	v_mfma_f32_16x16x32_bf16 v[112:115], v[178:181], v[186:189], v[112:115]
	v_mfma_f32_16x16x32_bf16 v[100:103], v[170:173], v[194:197], v[100:103]
	v_mfma_f32_16x16x32_bf16 v[96:99], v[178:181], v[194:197], v[96:99]
	v_mfma_f32_16x16x32_bf16 v[84:87], v[170:173], v[202:205], v[84:87]
	v_mfma_f32_16x16x32_bf16 v[80:83], v[178:181], v[202:205], v[80:83]
	v_mfma_f32_16x16x32_bf16 v[68:71], v[170:173], v[212:215], v[68:71]
	v_mfma_f32_16x16x32_bf16 v[64:67], v[178:181], v[212:215], v[64:67]
	s_barrier
	s_add_i32 s28, s51, s36
	s_mov_b32 m0, s28
	s_nop 0
	global_load_lds_dwordx4 v217, s[26:27]
	s_add_i32 m0, s28, 0x2000
	s_add_u32 s26, s26, 0x20080
	s_addc_u32 s27, s27, 0
	s_add_i32 s28, s52, s36
	global_load_lds_dwordx4 v219, s[98:99]
	s_mov_b32 m0, s28
	s_nop 0
	global_load_lds_dwordx4 v130, s[26:27]
	s_add_i32 m0, s28, 0x2000
	s_nop 0
	global_load_lds_dwordx4 v134, s[26:27]
	s_cmp_lg_u32 s50, 4
	s_cbranch_scc1 .Lbal_last_15
	s_mov_b32 m0, s41
	s_nop 0
	global_load_lds_dwordx4 v216, s[100:101]
	s_mov_b32 m0, s42
	s_nop 0
	global_load_lds_dwordx4 v218, s[100:101]

.Lbal_first_13:
	ds_read_b128 v[144:147], v151
	ds_read_b128 v[156:159], v151 offset:1024
	ds_read_b128 v[160:163], v151 offset:2048
	ds_read_b128 v[164:167], v151 offset:3072
	ds_read_b128 v[168:171], v152
	ds_read_b128 v[172:175], v152 offset:1024
	ds_read_b128 v[176:179], v152 offset:2048
	ds_read_b128 v[180:183], v152 offset:3072
	s_add_u32 s26, s24, 0xfffc0080
	s_addc_u32 s27, s25, -1
	s_cmp_eq_u32 s53, 12
	s_cselect_b32 s29, s19, s27
	s_cselect_b32 s28, s49, s26
	s_cselect_b32 s27, s17, s52
	s_cselect_b32 s26, s50, s51
	s_add_i32 m0, s39, 0xc000
	ds_read_b128 v[184:187], v153
	ds_read_b128 v[188:191], v153 offset:1024
	ds_read_b128 v[192:195], v153 offset:2048
	ds_read_b128 v[196:199], v153 offset:3072
	ds_read_b128 v[200:203], v153 offset:4096
	ds_read_b128 v[208:211], v153 offset:5120
	ds_read_b128 v[212:215], v153 offset:6144
	ds_read_b128 v[216:219], v153 offset:7168
	global_load_lds_dwordx4 v138, s[24:25]
	s_add_i32 m0, s39, 0xe000
	s_nop 0
	global_load_lds_dwordx4 v136, s[24:25]
	s_waitcnt vmcnt(8)
	s_waitcnt lgkmcnt(0)
	s_barrier
	s_waitcnt lgkmcnt(0)
	v_mfma_f32_16x16x32_bf16 v[124:127], v[144:147], v[184:187], v[124:127]
	v_mfma_f32_16x16x32_bf16 v[120:123], v[160:163], v[184:187], v[120:123]
	v_mfma_f32_16x16x32_bf16 v[108:111], v[144:147], v[192:195], v[108:111]
	v_mfma_f32_16x16x32_bf16 v[104:107], v[160:163], v[192:195], v[104:107]
	v_mfma_f32_16x16x32_bf16 v[92:95], v[144:147], v[200:203], v[92:95]
	v_mfma_f32_16x16x32_bf16 v[88:91], v[160:163], v[200:203], v[88:91]
	v_mfma_f32_16x16x32_bf16 v[76:79], v[144:147], v[212:215], v[76:79]
	v_mfma_f32_16x16x32_bf16 v[72:75], v[160:163], v[212:215], v[72:75]
	v_mfma_f32_16x16x32_bf16 v[124:127], v[156:159], v[188:191], v[124:127]
	v_mfma_f32_16x16x32_bf16 v[120:123], v[164:167], v[188:191], v[120:123]
	v_mfma_f32_16x16x32_bf16 v[108:111], v[156:159], v[196:199], v[108:111]
	v_mfma_f32_16x16x32_bf16 v[104:107], v[164:167], v[196:199], v[104:107]
	v_mfma_f32_16x16x32_bf16 v[92:95], v[156:159], v[208:211], v[92:95]
	v_mfma_f32_16x16x32_bf16 v[88:91], v[164:167], v[208:211], v[88:91]
	v_mfma_f32_16x16x32_bf16 v[76:79], v[156:159], v[216:219], v[76:79]
	v_mfma_f32_16x16x32_bf16 v[72:75], v[164:167], v[216:219], v[72:75]
	v_mfma_f32_16x16x32_bf16 v[116:119], v[168:171], v[184:187], v[116:119]
	v_mfma_f32_16x16x32_bf16 v[112:115], v[176:179], v[184:187], v[112:115]
	v_mfma_f32_16x16x32_bf16 v[100:103], v[168:171], v[192:195], v[100:103]
	v_mfma_f32_16x16x32_bf16 v[96:99], v[176:179], v[192:195], v[96:99]
	v_mfma_f32_16x16x32_bf16 v[84:87], v[168:171], v[200:203], v[84:87]
	v_mfma_f32_16x16x32_bf16 v[80:83], v[176:179], v[200:203], v[80:83]
	v_mfma_f32_16x16x32_bf16 v[68:71], v[168:171], v[212:215], v[68:71]
	v_mfma_f32_16x16x32_bf16 v[64:67], v[176:179], v[212:215], v[64:67]
	v_mfma_f32_16x16x32_bf16 v[116:119], v[172:175], v[188:191], v[116:119]
	v_mfma_f32_16x16x32_bf16 v[112:115], v[180:183], v[188:191], v[112:115]
	v_mfma_f32_16x16x32_bf16 v[100:103], v[172:175], v[196:199], v[100:103]
	v_mfma_f32_16x16x32_bf16 v[96:99], v[180:183], v[196:199], v[96:99]
	v_mfma_f32_16x16x32_bf16 v[84:87], v[172:175], v[208:211], v[84:87]
	v_mfma_f32_16x16x32_bf16 v[80:83], v[180:183], v[208:211], v[80:83]
	v_mfma_f32_16x16x32_bf16 v[68:71], v[172:175], v[216:219], v[68:71]
	v_mfma_f32_16x16x32_bf16 v[64:67], v[180:183], v[216:219], v[64:67]
	s_barrier
	s_add_i32 s54, s46, s38
	s_mov_b32 m0, s54
	s_nop 0
	global_load_lds_dwordx4 v130, s[26:27]
	s_add_i32 m0, s54, 0x2000
	s_add_u32 s54, s26, 0x40000
	s_mov_b64 s[98:99], s[26:27]
	s_addc_u32 s55, s27, 0
	s_add_i32 s56, s47, s38
	global_load_lds_dwordx4 v134, s[26:27]
	s_mov_b32 m0, s56
	s_mov_b64 s[100:101], s[28:29]
	global_load_lds_dwordx4 v130, s[54:55]
	s_add_i32 m0, s56, 0x2000
	s_nop 0
	global_load_lds_dwordx4 v134, s[54:55]
	ds_read_b128 v[184:187], v153 offset:16384
	ds_read_b128 v[188:191], v153 offset:17408
	ds_read_b128 v[192:195], v153 offset:18432
	ds_read_b128 v[196:199], v153 offset:19456
	ds_read_b128 v[200:203], v153 offset:20480
	ds_read_b128 v[208:211], v153 offset:21504
	ds_read_b128 v[212:215], v153 offset:22528
	ds_read_b128 v[216:219], v153 offset:23552
	s_waitcnt vmcnt(6)
	s_waitcnt lgkmcnt(0)
	s_barrier
	s_waitcnt lgkmcnt(0)
	v_mfma_f32_16x16x32_bf16 v[60:63], v[144:147], v[184:187], v[60:63]
	v_mfma_f32_16x16x32_bf16 v[56:59], v[160:163], v[184:187], v[56:59]
	v_mfma_f32_16x16x32_bf16 v[44:47], v[144:147], v[192:195], v[44:47]
	v_mfma_f32_16x16x32_bf16 v[40:43], v[160:163], v[192:195], v[40:43]
	v_mfma_f32_16x16x32_bf16 v[28:31], v[144:147], v[200:203], v[28:31]
	v_mfma_f32_16x16x32_bf16 v[24:27], v[160:163], v[200:203], v[24:27]
	v_mfma_f32_16x16x32_bf16 v[12:15], v[144:147], v[212:215], v[12:15]
	v_mfma_f32_16x16x32_bf16 v[8:11], v[160:163], v[212:215], v[8:11]
	v_mfma_f32_16x16x32_bf16 v[60:63], v[156:159], v[188:191], v[60:63]
	v_mfma_f32_16x16x32_bf16 v[56:59], v[164:167], v[188:191], v[56:59]
	v_mfma_f32_16x16x32_bf16 v[44:47], v[156:159], v[196:199], v[44:47]
	v_mfma_f32_16x16x32_bf16 v[40:43], v[164:167], v[196:199], v[40:43]
	v_mfma_f32_16x16x32_bf16 v[28:31], v[156:159], v[208:211], v[28:31]
	v_mfma_f32_16x16x32_bf16 v[24:27], v[164:167], v[208:211], v[24:27]
	v_mfma_f32_16x16x32_bf16 v[12:15], v[156:159], v[216:219], v[12:15]
	v_mfma_f32_16x16x32_bf16 v[8:11], v[164:167], v[216:219], v[8:11]
	v_mfma_f32_16x16x32_bf16 v[52:55], v[168:171], v[184:187], v[52:55]
	v_mfma_f32_16x16x32_bf16 v[48:51], v[176:179], v[184:187], v[48:51]
	v_mfma_f32_16x16x32_bf16 v[36:39], v[168:171], v[192:195], v[36:39]
	v_mfma_f32_16x16x32_bf16 v[32:35], v[176:179], v[192:195], v[32:35]
	v_mfma_f32_16x16x32_bf16 v[20:23], v[168:171], v[200:203], v[20:23]
	v_mfma_f32_16x16x32_bf16 v[16:19], v[176:179], v[200:203], v[16:19]
	v_mfma_f32_16x16x32_bf16 v[4:7], v[168:171], v[212:215], v[4:7]
	v_mfma_f32_16x16x32_bf16 v[0:3], v[176:179], v[212:215], v[0:3]
	v_mfma_f32_16x16x32_bf16 v[52:55], v[172:175], v[188:191], v[52:55]
	v_mfma_f32_16x16x32_bf16 v[48:51], v[180:183], v[188:191], v[48:51]
	v_mfma_f32_16x16x32_bf16 v[36:39], v[172:175], v[196:199], v[36:39]
	v_mfma_f32_16x16x32_bf16 v[32:35], v[180:183], v[196:199], v[32:35]
	v_mfma_f32_16x16x32_bf16 v[20:23], v[172:175], v[208:211], v[20:23]
	v_mfma_f32_16x16x32_bf16 v[16:19], v[180:183], v[208:211], v[16:19]
	v_mfma_f32_16x16x32_bf16 v[4:7], v[172:175], v[216:219], v[4:7]
	v_mfma_f32_16x16x32_bf16 v[0:3], v[180:183], v[216:219], v[0:3]
	s_barrier
	s_mov_b32 m0, s39
	s_nop 0
	global_load_lds_dwordx4 v128, s[28:29]
	s_mov_b32 m0, s40
	s_nop 0
	global_load_lds_dwordx4 v132, s[28:29]
	s_add_i32 s54, 0, 0x18000
	v_add_u32_e32 v155, s54, v149
	s_add_i32 s55, 0, 0x1c000
	ds_read_b128 v[144:147], v155
	ds_read_b128 v[156:159], v155 offset:1024
	ds_read_b128 v[160:163], v155 offset:2048
	ds_read_b128 v[164:167], v155 offset:3072
	v_add_u32_e32 v155, s55, v149
	ds_read_b128 v[168:171], v155
	ds_read_b128 v[172:175], v155 offset:1024
	ds_read_b128 v[176:179], v155 offset:2048
	ds_read_b128 v[180:183], v155 offset:3072
	s_add_u32 s28, s28, 0x40000
	s_addc_u32 s29, s29, 0
	s_mov_b32 m0, s41
	ds_read_b128 v[184:187], v153 offset:32768
	ds_read_b128 v[188:191], v153 offset:33792
	ds_read_b128 v[192:195], v153 offset:34816
	ds_read_b128 v[196:199], v153 offset:35840
	ds_read_b128 v[200:203], v153 offset:36864
	ds_read_b128 v[208:211], v153 offset:37888
	ds_read_b128 v[212:215], v153 offset:38912
	ds_read_b128 v[216:219], v153 offset:39936
	global_load_lds_dwordx4 v128, s[28:29]
	s_mov_b32 m0, s42
	s_nop 0
	global_load_lds_dwordx4 v132, s[28:29]
	s_waitcnt vmcnt(8)
	s_waitcnt lgkmcnt(0)
	s_barrier
	s_waitcnt lgkmcnt(0)
	v_mfma_f32_16x16x32_bf16 v[124:127], v[144:147], v[184:187], v[124:127]
	v_mfma_f32_16x16x32_bf16 v[120:123], v[160:163], v[184:187], v[120:123]
	v_mfma_f32_16x16x32_bf16 v[108:111], v[144:147], v[192:195], v[108:111]
	v_mfma_f32_16x16x32_bf16 v[104:107], v[160:163], v[192:195], v[104:107]
	v_mfma_f32_16x16x32_bf16 v[92:95], v[144:147], v[200:203], v[92:95]
	v_mfma_f32_16x16x32_bf16 v[88:91], v[160:163], v[200:203], v[88:91]
	v_mfma_f32_16x16x32_bf16 v[76:79], v[144:147], v[212:215], v[76:79]
	v_mfma_f32_16x16x32_bf16 v[72:75], v[160:163], v[212:215], v[72:75]
	v_mfma_f32_16x16x32_bf16 v[124:127], v[156:159], v[188:191], v[124:127]
	v_mfma_f32_16x16x32_bf16 v[120:123], v[164:167], v[188:191], v[120:123]
	v_mfma_f32_16x16x32_bf16 v[108:111], v[156:159], v[196:199], v[108:111]
	v_mfma_f32_16x16x32_bf16 v[104:107], v[164:167], v[196:199], v[104:107]
	v_mfma_f32_16x16x32_bf16 v[92:95], v[156:159], v[208:211], v[92:95]
	v_mfma_f32_16x16x32_bf16 v[88:91], v[164:167], v[208:211], v[88:91]
	v_mfma_f32_16x16x32_bf16 v[76:79], v[156:159], v[216:219], v[76:79]
	v_mfma_f32_16x16x32_bf16 v[72:75], v[164:167], v[216:219], v[72:75]
	v_mfma_f32_16x16x32_bf16 v[116:119], v[168:171], v[184:187], v[116:119]
	v_mfma_f32_16x16x32_bf16 v[112:115], v[176:179], v[184:187], v[112:115]
	v_mfma_f32_16x16x32_bf16 v[100:103], v[168:171], v[192:195], v[100:103]
	v_mfma_f32_16x16x32_bf16 v[96:99], v[176:179], v[192:195], v[96:99]
	v_mfma_f32_16x16x32_bf16 v[84:87], v[168:171], v[200:203], v[84:87]
	v_mfma_f32_16x16x32_bf16 v[80:83], v[176:179], v[200:203], v[80:83]
	v_mfma_f32_16x16x32_bf16 v[68:71], v[168:171], v[212:215], v[68:71]
	v_mfma_f32_16x16x32_bf16 v[64:67], v[176:179], v[212:215], v[64:67]
	v_mfma_f32_16x16x32_bf16 v[116:119], v[172:175], v[188:191], v[116:119]
	v_mfma_f32_16x16x32_bf16 v[112:115], v[180:183], v[188:191], v[112:115]
	v_mfma_f32_16x16x32_bf16 v[100:103], v[172:175], v[196:199], v[100:103]
	v_mfma_f32_16x16x32_bf16 v[96:99], v[180:183], v[196:199], v[96:99]
	v_mfma_f32_16x16x32_bf16 v[84:87], v[172:175], v[208:211], v[84:87]
	v_mfma_f32_16x16x32_bf16 v[80:83], v[180:183], v[208:211], v[80:83]
	v_mfma_f32_16x16x32_bf16 v[68:71], v[172:175], v[216:219], v[68:71]
	v_mfma_f32_16x16x32_bf16 v[64:67], v[180:183], v[216:219], v[64:67]
	s_barrier
	s_add_i32 s28, s54, s38
	s_mov_b32 m0, s28
	s_nop 0
	global_load_lds_dwordx4 v205, s[26:27]
	s_add_i32 m0, s28, 0x2000
	s_add_u32 s26, s26, 0x40080
	s_addc_u32 s27, s27, 0
	s_add_i32 s28, s55, s38
	global_load_lds_dwordx4 v221, s[98:99]
	s_mov_b32 m0, s28
	s_nop 0
	global_load_lds_dwordx4 v130, s[26:27]
	s_add_i32 m0, s28, 0x2000
	s_nop 0
	global_load_lds_dwordx4 v134, s[26:27]
	s_cmp_lg_u32 s53, 12
	s_cbranch_scc1 .Lbal_last_13
	s_mov_b32 m0, s44
	s_nop 0
	global_load_lds_dwordx4 v204, s[100:101]
	s_mov_b32 m0, s45
	s_nop 0
	global_load_lds_dwordx4 v220, s[100:101]

.Lbal_first_11:
	ds_read_b128 v[140:143], v151
	ds_read_b128 v[144:147], v151 offset:1024
	ds_read_b128 v[156:159], v151 offset:2048
	ds_read_b128 v[160:163], v151 offset:3072
	ds_read_b128 v[164:167], v152
	ds_read_b128 v[168:171], v152 offset:1024
	ds_read_b128 v[172:175], v152 offset:2048
	ds_read_b128 v[176:179], v152 offset:3072
	s_add_u32 s38, s36, 0xfffc0080
	s_addc_u32 s39, s37, -1
	s_cmp_eq_u32 s61, 12
	s_cselect_b32 s41, s3, s39
	s_cselect_b32 s40, s29, s38
	s_cselect_b32 s39, s27, s60
	s_cselect_b32 s38, s58, s59
	s_add_i32 m0, s46, 0xc000
	ds_read_b128 v[180:183], v153
	ds_read_b128 v[184:187], v153 offset:1024
	ds_read_b128 v[188:191], v153 offset:2048
	ds_read_b128 v[192:195], v153 offset:3072
	ds_read_b128 v[196:199], v153 offset:4096
	ds_read_b128 v[200:203], v153 offset:5120
	ds_read_b128 v[208:211], v153 offset:6144
	ds_read_b128 v[212:215], v153 offset:7168
	global_load_lds_dwordx4 v134, s[36:37]
	s_add_i32 m0, s46, 0xe000
	s_nop 0
	global_load_lds_dwordx4 v132, s[36:37]
	s_waitcnt vmcnt(8)
	s_waitcnt lgkmcnt(0)
	s_barrier
	s_waitcnt lgkmcnt(0)
	v_mfma_f32_16x16x32_bf16 v[124:127], v[140:143], v[180:183], v[124:127]
	v_mfma_f32_16x16x32_bf16 v[120:123], v[156:159], v[180:183], v[120:123]
	v_mfma_f32_16x16x32_bf16 v[108:111], v[140:143], v[188:191], v[108:111]
	v_mfma_f32_16x16x32_bf16 v[104:107], v[156:159], v[188:191], v[104:107]
	v_mfma_f32_16x16x32_bf16 v[92:95], v[140:143], v[196:199], v[92:95]
	v_mfma_f32_16x16x32_bf16 v[88:91], v[156:159], v[196:199], v[88:91]
	v_mfma_f32_16x16x32_bf16 v[76:79], v[140:143], v[208:211], v[76:79]
	v_mfma_f32_16x16x32_bf16 v[72:75], v[156:159], v[208:211], v[72:75]
	v_mfma_f32_16x16x32_bf16 v[124:127], v[144:147], v[184:187], v[124:127]
	v_mfma_f32_16x16x32_bf16 v[120:123], v[160:163], v[184:187], v[120:123]
	v_mfma_f32_16x16x32_bf16 v[108:111], v[144:147], v[192:195], v[108:111]
	v_mfma_f32_16x16x32_bf16 v[104:107], v[160:163], v[192:195], v[104:107]
	v_mfma_f32_16x16x32_bf16 v[92:95], v[144:147], v[200:203], v[92:95]
	v_mfma_f32_16x16x32_bf16 v[88:91], v[160:163], v[200:203], v[88:91]
	v_mfma_f32_16x16x32_bf16 v[76:79], v[144:147], v[212:215], v[76:79]
	v_mfma_f32_16x16x32_bf16 v[72:75], v[160:163], v[212:215], v[72:75]
	v_mfma_f32_16x16x32_bf16 v[116:119], v[164:167], v[180:183], v[116:119]
	v_mfma_f32_16x16x32_bf16 v[112:115], v[172:175], v[180:183], v[112:115]
	v_mfma_f32_16x16x32_bf16 v[100:103], v[164:167], v[188:191], v[100:103]
	v_mfma_f32_16x16x32_bf16 v[96:99], v[172:175], v[188:191], v[96:99]
	v_mfma_f32_16x16x32_bf16 v[84:87], v[164:167], v[196:199], v[84:87]
	v_mfma_f32_16x16x32_bf16 v[80:83], v[172:175], v[196:199], v[80:83]
	v_mfma_f32_16x16x32_bf16 v[68:71], v[164:167], v[208:211], v[68:71]
	v_mfma_f32_16x16x32_bf16 v[64:67], v[172:175], v[208:211], v[64:67]
	v_mfma_f32_16x16x32_bf16 v[116:119], v[168:171], v[184:187], v[116:119]
	v_mfma_f32_16x16x32_bf16 v[112:115], v[176:179], v[184:187], v[112:115]
	v_mfma_f32_16x16x32_bf16 v[100:103], v[168:171], v[192:195], v[100:103]
	v_mfma_f32_16x16x32_bf16 v[96:99], v[176:179], v[192:195], v[96:99]
	v_mfma_f32_16x16x32_bf16 v[84:87], v[168:171], v[200:203], v[84:87]
	v_mfma_f32_16x16x32_bf16 v[80:83], v[176:179], v[200:203], v[80:83]
	v_mfma_f32_16x16x32_bf16 v[68:71], v[168:171], v[212:215], v[68:71]
	v_mfma_f32_16x16x32_bf16 v[64:67], v[176:179], v[212:215], v[64:67]
	s_barrier
	s_add_i32 s62, s54, s45
	s_mov_b32 m0, s62
	s_nop 0
	global_load_lds_dwordx4 v128, s[38:39]
	s_add_i32 m0, s62, 0x2000
	s_add_u32 s62, s38, 0x40000
	s_mov_b64 s[98:99], s[38:39]
	s_addc_u32 s63, s39, 0
	s_add_i32 s64, s55, s45
	global_load_lds_dwordx4 v130, s[38:39]
	s_mov_b32 m0, s64
	s_mov_b64 s[100:101], s[40:41]
	global_load_lds_dwordx4 v128, s[62:63]
	s_add_i32 m0, s64, 0x2000
	s_nop 0
	global_load_lds_dwordx4 v130, s[62:63]
	ds_read_b128 v[180:183], v153 offset:16384
	ds_read_b128 v[184:187], v153 offset:17408
	ds_read_b128 v[188:191], v153 offset:18432
	ds_read_b128 v[192:195], v153 offset:19456
	ds_read_b128 v[196:199], v153 offset:20480
	ds_read_b128 v[200:203], v153 offset:21504
	ds_read_b128 v[208:211], v153 offset:22528
	ds_read_b128 v[212:215], v153 offset:23552
	s_waitcnt vmcnt(6)
	s_waitcnt lgkmcnt(0)
	s_barrier
	s_waitcnt lgkmcnt(0)
	v_mfma_f32_16x16x32_bf16 v[60:63], v[140:143], v[180:183], v[60:63]
	v_mfma_f32_16x16x32_bf16 v[56:59], v[156:159], v[180:183], v[56:59]
	v_mfma_f32_16x16x32_bf16 v[44:47], v[140:143], v[188:191], v[44:47]
	v_mfma_f32_16x16x32_bf16 v[40:43], v[156:159], v[188:191], v[40:43]
	v_mfma_f32_16x16x32_bf16 v[28:31], v[140:143], v[196:199], v[28:31]
	v_mfma_f32_16x16x32_bf16 v[24:27], v[156:159], v[196:199], v[24:27]
	v_mfma_f32_16x16x32_bf16 v[12:15], v[140:143], v[208:211], v[12:15]
	v_mfma_f32_16x16x32_bf16 v[8:11], v[156:159], v[208:211], v[8:11]
	v_mfma_f32_16x16x32_bf16 v[60:63], v[144:147], v[184:187], v[60:63]
	v_mfma_f32_16x16x32_bf16 v[56:59], v[160:163], v[184:187], v[56:59]
	v_mfma_f32_16x16x32_bf16 v[44:47], v[144:147], v[192:195], v[44:47]
	v_mfma_f32_16x16x32_bf16 v[40:43], v[160:163], v[192:195], v[40:43]
	v_mfma_f32_16x16x32_bf16 v[28:31], v[144:147], v[200:203], v[28:31]
	v_mfma_f32_16x16x32_bf16 v[24:27], v[160:163], v[200:203], v[24:27]
	v_mfma_f32_16x16x32_bf16 v[12:15], v[144:147], v[212:215], v[12:15]
	v_mfma_f32_16x16x32_bf16 v[8:11], v[160:163], v[212:215], v[8:11]
	v_mfma_f32_16x16x32_bf16 v[52:55], v[164:167], v[180:183], v[52:55]
	v_mfma_f32_16x16x32_bf16 v[48:51], v[172:175], v[180:183], v[48:51]
	v_mfma_f32_16x16x32_bf16 v[36:39], v[164:167], v[188:191], v[36:39]
	v_mfma_f32_16x16x32_bf16 v[32:35], v[172:175], v[188:191], v[32:35]
	v_mfma_f32_16x16x32_bf16 v[20:23], v[164:167], v[196:199], v[20:23]
	v_mfma_f32_16x16x32_bf16 v[16:19], v[172:175], v[196:199], v[16:19]
	v_mfma_f32_16x16x32_bf16 v[4:7], v[164:167], v[208:211], v[4:7]
	v_mfma_f32_16x16x32_bf16 v[0:3], v[172:175], v[208:211], v[0:3]
	v_mfma_f32_16x16x32_bf16 v[52:55], v[168:171], v[184:187], v[52:55]
	v_mfma_f32_16x16x32_bf16 v[48:51], v[176:179], v[184:187], v[48:51]
	v_mfma_f32_16x16x32_bf16 v[36:39], v[168:171], v[192:195], v[36:39]
	v_mfma_f32_16x16x32_bf16 v[32:35], v[176:179], v[192:195], v[32:35]
	v_mfma_f32_16x16x32_bf16 v[20:23], v[168:171], v[200:203], v[20:23]
	v_mfma_f32_16x16x32_bf16 v[16:19], v[176:179], v[200:203], v[16:19]
	v_mfma_f32_16x16x32_bf16 v[4:7], v[168:171], v[212:215], v[4:7]
	v_mfma_f32_16x16x32_bf16 v[0:3], v[176:179], v[212:215], v[0:3]
	s_barrier
	s_mov_b32 m0, s46
	s_nop 0
	global_load_lds_dwordx4 v128, s[40:41]
	s_mov_b32 m0, s47
	s_nop 0
	global_load_lds_dwordx4 v130, s[40:41]
	s_add_i32 s62, 0, 0x18000
	v_add_u32_e32 v155, s62, v149
	s_add_i32 s63, 0, 0x1c000
	ds_read_b128 v[140:143], v155
	ds_read_b128 v[144:147], v155 offset:1024
	ds_read_b128 v[156:159], v155 offset:2048
	ds_read_b128 v[160:163], v155 offset:3072
	v_add_u32_e32 v155, s63, v149
	ds_read_b128 v[164:167], v155
	ds_read_b128 v[168:171], v155 offset:1024
	ds_read_b128 v[172:175], v155 offset:2048
	ds_read_b128 v[176:179], v155 offset:3072
	s_add_u32 s40, s40, 0x40000
	s_addc_u32 s41, s41, 0
	s_mov_b32 m0, s48
	ds_read_b128 v[180:183], v153 offset:32768
	ds_read_b128 v[184:187], v153 offset:33792
	ds_read_b128 v[188:191], v153 offset:34816
	ds_read_b128 v[192:195], v153 offset:35840
	ds_read_b128 v[196:199], v153 offset:36864
	ds_read_b128 v[200:203], v153 offset:37888
	ds_read_b128 v[208:211], v153 offset:38912
	ds_read_b128 v[212:215], v153 offset:39936
	global_load_lds_dwordx4 v128, s[40:41]
	s_mov_b32 m0, s49
	s_nop 0
	global_load_lds_dwordx4 v130, s[40:41]
	s_waitcnt vmcnt(8)
	s_waitcnt lgkmcnt(0)
	s_barrier
	s_waitcnt lgkmcnt(0)
	v_mfma_f32_16x16x32_bf16 v[124:127], v[140:143], v[180:183], v[124:127]
	v_mfma_f32_16x16x32_bf16 v[120:123], v[156:159], v[180:183], v[120:123]
	v_mfma_f32_16x16x32_bf16 v[108:111], v[140:143], v[188:191], v[108:111]
	v_mfma_f32_16x16x32_bf16 v[104:107], v[156:159], v[188:191], v[104:107]
	v_mfma_f32_16x16x32_bf16 v[92:95], v[140:143], v[196:199], v[92:95]
	v_mfma_f32_16x16x32_bf16 v[88:91], v[156:159], v[196:199], v[88:91]
	v_mfma_f32_16x16x32_bf16 v[76:79], v[140:143], v[208:211], v[76:79]
	v_mfma_f32_16x16x32_bf16 v[72:75], v[156:159], v[208:211], v[72:75]
	v_mfma_f32_16x16x32_bf16 v[124:127], v[144:147], v[184:187], v[124:127]
	v_mfma_f32_16x16x32_bf16 v[120:123], v[160:163], v[184:187], v[120:123]
	v_mfma_f32_16x16x32_bf16 v[108:111], v[144:147], v[192:195], v[108:111]
	v_mfma_f32_16x16x32_bf16 v[104:107], v[160:163], v[192:195], v[104:107]
	v_mfma_f32_16x16x32_bf16 v[92:95], v[144:147], v[200:203], v[92:95]
	v_mfma_f32_16x16x32_bf16 v[88:91], v[160:163], v[200:203], v[88:91]
	v_mfma_f32_16x16x32_bf16 v[76:79], v[144:147], v[212:215], v[76:79]
	v_mfma_f32_16x16x32_bf16 v[72:75], v[160:163], v[212:215], v[72:75]
	v_mfma_f32_16x16x32_bf16 v[116:119], v[164:167], v[180:183], v[116:119]
	v_mfma_f32_16x16x32_bf16 v[112:115], v[172:175], v[180:183], v[112:115]
	v_mfma_f32_16x16x32_bf16 v[100:103], v[164:167], v[188:191], v[100:103]
	v_mfma_f32_16x16x32_bf16 v[96:99], v[172:175], v[188:191], v[96:99]
	v_mfma_f32_16x16x32_bf16 v[84:87], v[164:167], v[196:199], v[84:87]
	v_mfma_f32_16x16x32_bf16 v[80:83], v[172:175], v[196:199], v[80:83]
	v_mfma_f32_16x16x32_bf16 v[68:71], v[164:167], v[208:211], v[68:71]
	v_mfma_f32_16x16x32_bf16 v[64:67], v[172:175], v[208:211], v[64:67]
	v_mfma_f32_16x16x32_bf16 v[116:119], v[168:171], v[184:187], v[116:119]
	v_mfma_f32_16x16x32_bf16 v[112:115], v[176:179], v[184:187], v[112:115]
	v_mfma_f32_16x16x32_bf16 v[100:103], v[168:171], v[192:195], v[100:103]
	v_mfma_f32_16x16x32_bf16 v[96:99], v[176:179], v[192:195], v[96:99]
	v_mfma_f32_16x16x32_bf16 v[84:87], v[168:171], v[200:203], v[84:87]
	v_mfma_f32_16x16x32_bf16 v[80:83], v[176:179], v[200:203], v[80:83]
	v_mfma_f32_16x16x32_bf16 v[68:71], v[168:171], v[212:215], v[68:71]
	v_mfma_f32_16x16x32_bf16 v[64:67], v[176:179], v[212:215], v[64:67]
	s_barrier
	s_add_i32 s40, s62, s45
	s_mov_b32 m0, s40
	s_nop 0
	global_load_lds_dwordx4 v204, s[38:39]
	s_add_i32 m0, s40, 0x2000
	s_add_u32 s38, s38, 0x40080
	s_addc_u32 s39, s39, 0
	s_add_i32 s40, s63, s45
	global_load_lds_dwordx4 v205, s[98:99]
	s_mov_b32 m0, s40
	s_nop 0
	global_load_lds_dwordx4 v128, s[38:39]
	s_add_i32 m0, s40, 0x2000
	s_nop 0
	global_load_lds_dwordx4 v130, s[38:39]
	s_cmp_lg_u32 s61, 12
	s_cbranch_scc1 .Lbal_last_11
	s_mov_b32 m0, s51
	s_nop 0
	global_load_lds_dwordx4 v204, s[100:101]
	s_mov_b32 m0, s52
	s_nop 0
	global_load_lds_dwordx4 v205, s[100:101]

.Lbal_first_10:
	ds_read_b128 v[144:147], v151
	ds_read_b128 v[156:159], v151 offset:1024
	ds_read_b128 v[160:163], v151 offset:2048
	ds_read_b128 v[164:167], v151 offset:3072
	ds_read_b128 v[168:171], v152
	ds_read_b128 v[172:175], v152 offset:1024
	ds_read_b128 v[176:179], v152 offset:2048
	ds_read_b128 v[180:183], v152 offset:3072
	s_add_u32 s26, s24, 0xfffc0080
	s_addc_u32 s27, s25, -1
	s_cmp_eq_u32 s54, 12
	s_cselect_b32 s29, s19, s27
	s_cselect_b32 s28, s50, s26
	s_cselect_b32 s27, s17, s53
	s_cselect_b32 s26, s51, s52
	s_add_i32 m0, s38, 0xc000
	ds_read_b128 v[184:187], v153
	ds_read_b128 v[188:191], v153 offset:1024
	ds_read_b128 v[192:195], v153 offset:2048
	ds_read_b128 v[196:199], v153 offset:3072
	ds_read_b128 v[200:203], v153 offset:4096
	ds_read_b128 v[208:211], v153 offset:5120
	ds_read_b128 v[212:215], v153 offset:6144
	ds_read_b128 v[216:219], v153 offset:7168
	global_load_lds_dwordx4 v138, s[24:25]
	s_add_i32 m0, s38, 0xe000
	s_nop 0
	global_load_lds_dwordx4 v136, s[24:25]
	s_waitcnt vmcnt(8)
	s_waitcnt lgkmcnt(0)
	s_barrier
	s_waitcnt lgkmcnt(0)
	v_mfma_f32_16x16x32_bf16 v[124:127], v[144:147], v[184:187], v[124:127]
	v_mfma_f32_16x16x32_bf16 v[120:123], v[160:163], v[184:187], v[120:123]
	v_mfma_f32_16x16x32_bf16 v[108:111], v[144:147], v[192:195], v[108:111]
	v_mfma_f32_16x16x32_bf16 v[104:107], v[160:163], v[192:195], v[104:107]
	v_mfma_f32_16x16x32_bf16 v[92:95], v[144:147], v[200:203], v[92:95]
	v_mfma_f32_16x16x32_bf16 v[88:91], v[160:163], v[200:203], v[88:91]
	v_mfma_f32_16x16x32_bf16 v[76:79], v[144:147], v[212:215], v[76:79]
	v_mfma_f32_16x16x32_bf16 v[72:75], v[160:163], v[212:215], v[72:75]
	v_mfma_f32_16x16x32_bf16 v[124:127], v[156:159], v[188:191], v[124:127]
	v_mfma_f32_16x16x32_bf16 v[120:123], v[164:167], v[188:191], v[120:123]
	v_mfma_f32_16x16x32_bf16 v[108:111], v[156:159], v[196:199], v[108:111]
	v_mfma_f32_16x16x32_bf16 v[104:107], v[164:167], v[196:199], v[104:107]
	v_mfma_f32_16x16x32_bf16 v[92:95], v[156:159], v[208:211], v[92:95]
	v_mfma_f32_16x16x32_bf16 v[88:91], v[164:167], v[208:211], v[88:91]
	v_mfma_f32_16x16x32_bf16 v[76:79], v[156:159], v[216:219], v[76:79]
	v_mfma_f32_16x16x32_bf16 v[72:75], v[164:167], v[216:219], v[72:75]
	v_mfma_f32_16x16x32_bf16 v[116:119], v[168:171], v[184:187], v[116:119]
	v_mfma_f32_16x16x32_bf16 v[112:115], v[176:179], v[184:187], v[112:115]
	v_mfma_f32_16x16x32_bf16 v[100:103], v[168:171], v[192:195], v[100:103]
	v_mfma_f32_16x16x32_bf16 v[96:99], v[176:179], v[192:195], v[96:99]
	v_mfma_f32_16x16x32_bf16 v[84:87], v[168:171], v[200:203], v[84:87]
	v_mfma_f32_16x16x32_bf16 v[80:83], v[176:179], v[200:203], v[80:83]
	v_mfma_f32_16x16x32_bf16 v[68:71], v[168:171], v[212:215], v[68:71]
	v_mfma_f32_16x16x32_bf16 v[64:67], v[176:179], v[212:215], v[64:67]
	v_mfma_f32_16x16x32_bf16 v[116:119], v[172:175], v[188:191], v[116:119]
	v_mfma_f32_16x16x32_bf16 v[112:115], v[180:183], v[188:191], v[112:115]
	v_mfma_f32_16x16x32_bf16 v[100:103], v[172:175], v[196:199], v[100:103]
	v_mfma_f32_16x16x32_bf16 v[96:99], v[180:183], v[196:199], v[96:99]
	v_mfma_f32_16x16x32_bf16 v[84:87], v[172:175], v[208:211], v[84:87]
	v_mfma_f32_16x16x32_bf16 v[80:83], v[180:183], v[208:211], v[80:83]
	v_mfma_f32_16x16x32_bf16 v[68:71], v[172:175], v[216:219], v[68:71]
	v_mfma_f32_16x16x32_bf16 v[64:67], v[180:183], v[216:219], v[64:67]
	s_barrier
	s_add_i32 s55, s47, s35
	s_mov_b32 m0, s55
	s_nop 0
	global_load_lds_dwordx4 v132, s[26:27]
	s_add_i32 m0, s55, 0x2000
	s_add_u32 s56, s26, 0x40000
	s_mov_b64 s[98:99], s[26:27]
	s_addc_u32 s57, s27, 0
	s_add_i32 s55, s48, s35
	global_load_lds_dwordx4 v128, s[26:27]
	s_mov_b32 m0, s55
	s_mov_b64 s[100:101], s[28:29]
	global_load_lds_dwordx4 v132, s[56:57]
	s_add_i32 m0, s55, 0x2000
	s_nop 0
	global_load_lds_dwordx4 v128, s[56:57]
	ds_read_b128 v[184:187], v153 offset:16384
	ds_read_b128 v[188:191], v153 offset:17408
	ds_read_b128 v[192:195], v153 offset:18432
	ds_read_b128 v[196:199], v153 offset:19456
	ds_read_b128 v[200:203], v153 offset:20480
	ds_read_b128 v[208:211], v153 offset:21504
	ds_read_b128 v[212:215], v153 offset:22528
	ds_read_b128 v[216:219], v153 offset:23552
	s_waitcnt vmcnt(6)
	s_waitcnt lgkmcnt(0)
	s_barrier
	s_waitcnt lgkmcnt(0)
	v_mfma_f32_16x16x32_bf16 v[60:63], v[144:147], v[184:187], v[60:63]
	v_mfma_f32_16x16x32_bf16 v[56:59], v[160:163], v[184:187], v[56:59]
	v_mfma_f32_16x16x32_bf16 v[44:47], v[144:147], v[192:195], v[44:47]
	v_mfma_f32_16x16x32_bf16 v[40:43], v[160:163], v[192:195], v[40:43]
	v_mfma_f32_16x16x32_bf16 v[28:31], v[144:147], v[200:203], v[28:31]
	v_mfma_f32_16x16x32_bf16 v[24:27], v[160:163], v[200:203], v[24:27]
	v_mfma_f32_16x16x32_bf16 v[12:15], v[144:147], v[212:215], v[12:15]
	v_mfma_f32_16x16x32_bf16 v[8:11], v[160:163], v[212:215], v[8:11]
	v_mfma_f32_16x16x32_bf16 v[60:63], v[156:159], v[188:191], v[60:63]
	v_mfma_f32_16x16x32_bf16 v[56:59], v[164:167], v[188:191], v[56:59]
	v_mfma_f32_16x16x32_bf16 v[44:47], v[156:159], v[196:199], v[44:47]
	v_mfma_f32_16x16x32_bf16 v[40:43], v[164:167], v[196:199], v[40:43]
	v_mfma_f32_16x16x32_bf16 v[28:31], v[156:159], v[208:211], v[28:31]
	v_mfma_f32_16x16x32_bf16 v[24:27], v[164:167], v[208:211], v[24:27]
	v_mfma_f32_16x16x32_bf16 v[12:15], v[156:159], v[216:219], v[12:15]
	v_mfma_f32_16x16x32_bf16 v[8:11], v[164:167], v[216:219], v[8:11]
	v_mfma_f32_16x16x32_bf16 v[52:55], v[168:171], v[184:187], v[52:55]
	v_mfma_f32_16x16x32_bf16 v[48:51], v[176:179], v[184:187], v[48:51]
	v_mfma_f32_16x16x32_bf16 v[36:39], v[168:171], v[192:195], v[36:39]
	v_mfma_f32_16x16x32_bf16 v[32:35], v[176:179], v[192:195], v[32:35]
	v_mfma_f32_16x16x32_bf16 v[20:23], v[168:171], v[200:203], v[20:23]
	v_mfma_f32_16x16x32_bf16 v[16:19], v[176:179], v[200:203], v[16:19]
	v_mfma_f32_16x16x32_bf16 v[4:7], v[168:171], v[212:215], v[4:7]
	v_mfma_f32_16x16x32_bf16 v[0:3], v[176:179], v[212:215], v[0:3]
	v_mfma_f32_16x16x32_bf16 v[52:55], v[172:175], v[188:191], v[52:55]
	v_mfma_f32_16x16x32_bf16 v[48:51], v[180:183], v[188:191], v[48:51]
	v_mfma_f32_16x16x32_bf16 v[36:39], v[172:175], v[196:199], v[36:39]
	v_mfma_f32_16x16x32_bf16 v[32:35], v[180:183], v[196:199], v[32:35]
	v_mfma_f32_16x16x32_bf16 v[20:23], v[172:175], v[208:211], v[20:23]
	v_mfma_f32_16x16x32_bf16 v[16:19], v[180:183], v[208:211], v[16:19]
	v_mfma_f32_16x16x32_bf16 v[4:7], v[172:175], v[216:219], v[4:7]
	v_mfma_f32_16x16x32_bf16 v[0:3], v[180:183], v[216:219], v[0:3]
	s_barrier
	s_mov_b32 m0, s38
	s_nop 0
	global_load_lds_dwordx4 v134, s[28:29]
	s_mov_b32 m0, s39
	s_nop 0
	global_load_lds_dwordx4 v130, s[28:29]
	s_add_i32 s55, 0, 0x18000
	s_add_i32 s56, 0, 0x1c000
	v_add_u32_e32 v164, s55, v149
	v_add_u32_e32 v180, s56, v149
	ds_read_b128 v[144:147], v164
	ds_read_b128 v[156:159], v164 offset:1024
	ds_read_b128 v[160:163], v164 offset:2048
	ds_read_b128 v[164:167], v164 offset:3072
	ds_read_b128 v[168:171], v180
	ds_read_b128 v[172:175], v180 offset:1024
	ds_read_b128 v[176:179], v180 offset:2048
	ds_read_b128 v[180:183], v180 offset:3072
	s_add_u32 s28, s28, 0x40000
	s_addc_u32 s29, s29, 0
	s_mov_b32 m0, s40
	ds_read_b128 v[184:187], v153 offset:32768
	ds_read_b128 v[188:191], v153 offset:33792
	ds_read_b128 v[192:195], v153 offset:34816
	ds_read_b128 v[196:199], v153 offset:35840
	ds_read_b128 v[200:203], v153 offset:36864
	ds_read_b128 v[208:211], v153 offset:37888
	ds_read_b128 v[212:215], v153 offset:38912
	ds_read_b128 v[216:219], v153 offset:39936
	global_load_lds_dwordx4 v134, s[28:29]
	s_mov_b32 m0, s41
	s_nop 0
	global_load_lds_dwordx4 v130, s[28:29]
	s_waitcnt vmcnt(8)
	s_waitcnt lgkmcnt(0)
	s_barrier
	s_waitcnt lgkmcnt(0)
	v_mfma_f32_16x16x32_bf16 v[124:127], v[144:147], v[184:187], v[124:127]
	v_mfma_f32_16x16x32_bf16 v[120:123], v[160:163], v[184:187], v[120:123]
	v_mfma_f32_16x16x32_bf16 v[108:111], v[144:147], v[192:195], v[108:111]
	v_mfma_f32_16x16x32_bf16 v[104:107], v[160:163], v[192:195], v[104:107]
	v_mfma_f32_16x16x32_bf16 v[92:95], v[144:147], v[200:203], v[92:95]
	v_mfma_f32_16x16x32_bf16 v[88:91], v[160:163], v[200:203], v[88:91]
	v_mfma_f32_16x16x32_bf16 v[76:79], v[144:147], v[212:215], v[76:79]
	v_mfma_f32_16x16x32_bf16 v[72:75], v[160:163], v[212:215], v[72:75]
	v_mfma_f32_16x16x32_bf16 v[124:127], v[156:159], v[188:191], v[124:127]
	v_mfma_f32_16x16x32_bf16 v[120:123], v[164:167], v[188:191], v[120:123]
	v_mfma_f32_16x16x32_bf16 v[108:111], v[156:159], v[196:199], v[108:111]
	v_mfma_f32_16x16x32_bf16 v[104:107], v[164:167], v[196:199], v[104:107]
	v_mfma_f32_16x16x32_bf16 v[92:95], v[156:159], v[208:211], v[92:95]
	v_mfma_f32_16x16x32_bf16 v[88:91], v[164:167], v[208:211], v[88:91]
	v_mfma_f32_16x16x32_bf16 v[76:79], v[156:159], v[216:219], v[76:79]
	v_mfma_f32_16x16x32_bf16 v[72:75], v[164:167], v[216:219], v[72:75]
	v_mfma_f32_16x16x32_bf16 v[116:119], v[168:171], v[184:187], v[116:119]
	v_mfma_f32_16x16x32_bf16 v[112:115], v[176:179], v[184:187], v[112:115]
	v_mfma_f32_16x16x32_bf16 v[100:103], v[168:171], v[192:195], v[100:103]
	v_mfma_f32_16x16x32_bf16 v[96:99], v[176:179], v[192:195], v[96:99]
	v_mfma_f32_16x16x32_bf16 v[84:87], v[168:171], v[200:203], v[84:87]
	v_mfma_f32_16x16x32_bf16 v[80:83], v[176:179], v[200:203], v[80:83]
	v_mfma_f32_16x16x32_bf16 v[68:71], v[168:171], v[212:215], v[68:71]
	v_mfma_f32_16x16x32_bf16 v[64:67], v[176:179], v[212:215], v[64:67]
	v_mfma_f32_16x16x32_bf16 v[116:119], v[172:175], v[188:191], v[116:119]
	v_mfma_f32_16x16x32_bf16 v[112:115], v[180:183], v[188:191], v[112:115]
	v_mfma_f32_16x16x32_bf16 v[100:103], v[172:175], v[196:199], v[100:103]
	v_mfma_f32_16x16x32_bf16 v[96:99], v[180:183], v[196:199], v[96:99]
	v_mfma_f32_16x16x32_bf16 v[84:87], v[172:175], v[208:211], v[84:87]
	v_mfma_f32_16x16x32_bf16 v[80:83], v[180:183], v[208:211], v[80:83]
	v_mfma_f32_16x16x32_bf16 v[68:71], v[172:175], v[216:219], v[68:71]
	v_mfma_f32_16x16x32_bf16 v[64:67], v[180:183], v[216:219], v[64:67]
	s_barrier
	s_add_i32 s28, s55, s35
	s_mov_b32 m0, s28
	s_nop 0
	global_load_lds_dwordx4 v220, s[26:27]
	s_add_i32 m0, s28, 0x2000
	s_add_u32 s26, s26, 0x40080
	s_addc_u32 s27, s27, 0
	s_add_i32 s28, s56, s35
	global_load_lds_dwordx4 v204, s[98:99]
	s_mov_b32 m0, s28
	s_nop 0
	global_load_lds_dwordx4 v132, s[26:27]
	s_add_i32 m0, s28, 0x2000
	s_nop 0
	global_load_lds_dwordx4 v128, s[26:27]
	s_cmp_lg_u32 s54, 12
	s_cbranch_scc1 .Lbal_last_10
	s_mov_b32 m0, s45
	s_nop 0
	global_load_lds_dwordx4 v221, s[100:101]
	s_mov_b32 m0, s46
	s_nop 0
	global_load_lds_dwordx4 v205, s[100:101]
